# EpiRes epilogues (FFN1-down, w_o, FFN2-down) hand-packed on raw accumulators, alpha folded into fma
# baseline (speedup 1.0000x reference)
; #define PG8_STAGE(bufoff, gbase, voff) do { _Pragma("unroll") for (int _i = 0; _i < 2; ++_i) \
;         __builtin_amdgcn_global_load_lds((const unsigned*)((const char*)(gbase) + (voff)[_i]), (PG8_LAS unsigned*)(lds + (bufoff) + ldsw + _i * 8192), 16, 0, 0); } while (0)
; #define PG8_LDA(dst, b, h) do { _Pragma("unroll") for (int m = 0; m < 4; ++m) _Pragma("unroll") for (int k = 0; k < 2; ++k) dst[m][k] = *(const PG8_LAS bf16x8*)(lds + PG8_SA(b, h) + aoff + m * 2048 + k * 1024); } while (0)
; #define PG8_LDB(dst, b, h) do { _Pragma("unroll") for (int n = 0; n < 2; ++n) _Pragma("unroll") for (int k = 0; k < 2; ++k) dst[n][k] = *(const PG8_LAS bf16x8*)(lds + PG8_SB(b, h) + boff + n * 2048 + k * 1024); } while (0)
; #define PG8_MMA(ai, bj, At, Bt) do { __builtin_amdgcn_s_setprio(1); _Pragma("unroll") for (int m = 0; m < 4; ++m) _Pragma("unroll") for (int n = 0; n < 2; ++n) _Pragma("unroll") for (int k = 0; k < 2; ++k) \
;         acc[ai][bj][m][n] = __builtin_amdgcn_mfma_f32_16x16x32_bf16(Bt[n][k], At[m][k], acc[ai][bj][m][n], 0, 0, 0); __builtin_amdgcn_s_setprio(0); } while (0)
; #define PG8_WAIT_V(n) asm volatile("s_waitcnt vmcnt(" #n ")" ::: "memory")
; #define PG8_BAR __builtin_amdgcn_s_barrier()
; template <class Epi, class Sched, bool ALIGN_EPI = false, bool SP2 = false>
; __device__ __forceinline__ void gemm_phase(PG8_LAS unsigned char* lds, const Gemm g, const Sched& S, const Epi& E) {
;     ...
;         for (int t = 0; t < nt; t += 2) {
;             const bool last = (t == nt - 2);
;             const char* a1 = cA + (size_t)(t + 1) * kstep;
;             const char* a2 = last ? nA : cA + (size_t)(t + 2) * kstep; const char* b2 = last ? nB : cB + (size_t)(t + 2) * kstep;
;             const char* a3 = a2 + kstep; const char* b3 = b2 + kstep;
;             if (last && has_next) S.a_ready(nxt);
;             if constexpr (SP2) {
;             PG8_LDB(B0, 0, 0); PG8_LDB(B1, 0, 1); PG8_SCHED; PG8_LDA(At, 0, 0); PG8_STAGE(PG8_SA(1, 1), a1 + hstep, voffA);
;             PG8_WAIT_V(8); PG8_WAIT_L(0); PG8_BAR; PG8_MMA(0, 0, At, B0); PG8_MMA(0, 1, At, B1); PG8_BAR; PG8_SCHED;
;     ...
; #pragma unroll
;         for (int a = 0; a < 2; ++a)
; #pragma unroll
;             for (int b = 0; b < 2; ++b)
; #pragma unroll
;                 for (int m = 0; m < 4; ++m)
; #pragma unroll
;                     for (int n = 0; n < 2; ++n) acc[a][b][m][n] = (f32x4){0.f, 0.f, 0.f, 0.f};
.LBB0_366:
	v_mov_b64_e32 v[0:1], 0
	v_mov_b64_e32 v[2:3], 0
	v_mov_b64_e32 v[4:5], 0
	v_mov_b64_e32 v[6:7], 0
	v_mov_b64_e32 v[8:9], 0
	v_mov_b64_e32 v[10:11], 0
	v_mov_b64_e32 v[12:13], 0
	v_mov_b64_e32 v[14:15], 0
	v_mov_b64_e32 v[16:17], 0
	v_mov_b64_e32 v[18:19], 0
	v_mov_b64_e32 v[20:21], 0
	v_mov_b64_e32 v[22:23], 0
	v_mov_b64_e32 v[24:25], 0
	v_mov_b64_e32 v[26:27], 0
	v_mov_b64_e32 v[28:29], 0
	v_mov_b64_e32 v[30:31], 0
	v_mov_b64_e32 v[32:33], 0
	v_mov_b64_e32 v[34:35], 0
	v_mov_b64_e32 v[36:37], 0
	v_mov_b64_e32 v[38:39], 0
	v_mov_b64_e32 v[40:41], 0
	v_mov_b64_e32 v[42:43], 0
	v_mov_b64_e32 v[44:45], 0
	v_mov_b64_e32 v[46:47], 0
	v_mov_b64_e32 v[48:49], 0
	v_mov_b64_e32 v[50:51], 0
	v_mov_b64_e32 v[52:53], 0
	v_mov_b64_e32 v[54:55], 0
	v_mov_b64_e32 v[56:57], 0
	v_mov_b64_e32 v[58:59], 0
	v_mov_b64_e32 v[60:61], 0
	v_mov_b64_e32 v[62:63], 0
	v_mov_b64_e32 v[64:65], 0
	v_mov_b64_e32 v[66:67], 0
	v_mov_b64_e32 v[68:69], 0
	v_mov_b64_e32 v[70:71], 0
	v_mov_b64_e32 v[72:73], 0
	v_mov_b64_e32 v[74:75], 0
	v_mov_b64_e32 v[76:77], 0
	v_mov_b64_e32 v[78:79], 0
	v_mov_b64_e32 v[80:81], 0
	v_mov_b64_e32 v[82:83], 0
	v_mov_b64_e32 v[84:85], 0
	v_mov_b64_e32 v[86:87], 0
	v_mov_b64_e32 v[88:89], 0
	v_mov_b64_e32 v[90:91], 0
	v_mov_b64_e32 v[92:93], 0
	v_mov_b64_e32 v[94:95], 0
	v_mov_b64_e32 v[96:97], 0
	v_mov_b64_e32 v[98:99], 0
	v_mov_b64_e32 v[100:101], 0
	v_mov_b64_e32 v[102:103], 0
	v_mov_b64_e32 v[104:105], 0
	v_mov_b64_e32 v[106:107], 0
	v_mov_b64_e32 v[108:109], 0
	v_mov_b64_e32 v[110:111], 0
	v_mov_b64_e32 v[112:113], 0
	v_mov_b64_e32 v[114:115], 0
	v_mov_b64_e32 v[116:117], 0
	v_mov_b64_e32 v[118:119], 0
	v_mov_b64_e32 v[120:121], 0
	v_mov_b64_e32 v[122:123], 0
	v_mov_b64_e32 v[124:125], 0
	v_mov_b64_e32 v[126:127], 0
	s_andn2_b64 vcc, exec, s[40:41]
	.p2align 8
	s_cbranch_vccnz .LBB0_370
	s_add_u32 s58, s58, 0x80
	s_addc_u32 s59, s59, 0
	s_add_u32 s4, s60, 0x100
	s_addc_u32 s5, s61, 0
	s_mov_b32 s33, 0
	s_waitcnt lgkmcnt(0)
	s_waitcnt vmcnt(0)
.LBB0_368:
	ds_read_b128 v[144:147], v248
	ds_read_b128 v[148:151], v248 offset:1024
	ds_read_b128 v[152:155], v248 offset:2048
	ds_read_b128 v[156:159], v248 offset:3072
	ds_read_b128 v[160:163], v249
	ds_read_b128 v[164:167], v249 offset:1024
	ds_read_b128 v[168:171], v249 offset:2048
	ds_read_b128 v[172:175], v249 offset:3072
	s_add_i32 s38, s33, 2
	s_add_u32 s60, s58, 0x80
	s_addc_u32 s61, s59, 0
	s_cmp_eq_u32 s68, s33
	s_cselect_b32 s61, s11, s61
	s_cselect_b32 s60, s10, s60
	s_cselect_b32 s79, s57, s5
	s_cselect_b32 s78, s56, s4
	v_lshl_add_u64 v[210:211], s[58:59], 0, v[138:139]
	s_add_i32 m0, s39, 0xc000
	ds_read_b128 v[176:179], v250
	ds_read_b128 v[180:183], v250 offset:1024
	ds_read_b128 v[184:187], v250 offset:2048
	ds_read_b128 v[188:191], v250 offset:3072
	ds_read_b128 v[194:197], v250 offset:4096
	ds_read_b128 v[198:201], v250 offset:5120
	ds_read_b128 v[202:205], v250 offset:6144
	ds_read_b128 v[206:209], v250 offset:7168
	global_load_lds_dwordx4 v[210:211], off
	v_lshl_add_u64 v[210:211], s[58:59], 0, v[140:141]
	s_add_i32 m0, s39, 0xe000
	s_nop 0
	global_load_lds_dwordx4 v[210:211], off
	s_waitcnt vmcnt(8)
	s_waitcnt lgkmcnt(0)
	s_barrier
	s_setprio 1
	s_waitcnt lgkmcnt(0)
	v_mfma_f32_16x16x32_bf16 v[124:127], v[144:147], v[176:179], v[124:127]
	v_mfma_f32_16x16x32_bf16 v[120:123], v[152:155], v[176:179], v[120:123]
	v_mfma_f32_16x16x32_bf16 v[116:119], v[144:147], v[184:187], v[116:119]
	v_mfma_f32_16x16x32_bf16 v[112:115], v[152:155], v[184:187], v[112:115]
	v_mfma_f32_16x16x32_bf16 v[104:107], v[144:147], v[194:197], v[104:107]
	v_mfma_f32_16x16x32_bf16 v[96:99], v[152:155], v[194:197], v[96:99]
	v_mfma_f32_16x16x32_bf16 v[88:91], v[144:147], v[202:205], v[88:91]
	v_mfma_f32_16x16x32_bf16 v[80:83], v[152:155], v[202:205], v[80:83]
	v_mfma_f32_16x16x32_bf16 v[124:127], v[148:151], v[180:183], v[124:127]
	v_mfma_f32_16x16x32_bf16 v[120:123], v[156:159], v[180:183], v[120:123]
	v_mfma_f32_16x16x32_bf16 v[116:119], v[148:151], v[188:191], v[116:119]
	v_mfma_f32_16x16x32_bf16 v[112:115], v[156:159], v[188:191], v[112:115]
	v_mfma_f32_16x16x32_bf16 v[104:107], v[148:151], v[198:201], v[104:107]
	v_mfma_f32_16x16x32_bf16 v[96:99], v[156:159], v[198:201], v[96:99]
	v_mfma_f32_16x16x32_bf16 v[88:91], v[148:151], v[206:209], v[88:91]
	v_mfma_f32_16x16x32_bf16 v[80:83], v[156:159], v[206:209], v[80:83]
	s_setprio 0
	s_setprio 1
	v_mfma_f32_16x16x32_bf16 v[108:111], v[160:163], v[176:179], v[108:111]
	v_mfma_f32_16x16x32_bf16 v[100:103], v[168:171], v[176:179], v[100:103]
	v_mfma_f32_16x16x32_bf16 v[92:95], v[160:163], v[184:187], v[92:95]
	v_mfma_f32_16x16x32_bf16 v[84:87], v[168:171], v[184:187], v[84:87]
	v_mfma_f32_16x16x32_bf16 v[76:79], v[160:163], v[194:197], v[76:79]
	v_mfma_f32_16x16x32_bf16 v[72:75], v[168:171], v[194:197], v[72:75]
	v_mfma_f32_16x16x32_bf16 v[68:71], v[160:163], v[202:205], v[68:71]
	v_mfma_f32_16x16x32_bf16 v[64:67], v[168:171], v[202:205], v[64:67]
	v_mfma_f32_16x16x32_bf16 v[108:111], v[164:167], v[180:183], v[108:111]
	v_mfma_f32_16x16x32_bf16 v[100:103], v[172:175], v[180:183], v[100:103]
	v_mfma_f32_16x16x32_bf16 v[92:95], v[164:167], v[188:191], v[92:95]
	v_mfma_f32_16x16x32_bf16 v[84:87], v[172:175], v[188:191], v[84:87]
	v_mfma_f32_16x16x32_bf16 v[76:79], v[164:167], v[198:201], v[76:79]
	v_mfma_f32_16x16x32_bf16 v[72:75], v[172:175], v[198:201], v[72:75]
	v_mfma_f32_16x16x32_bf16 v[68:71], v[164:167], v[206:209], v[68:71]
	v_mfma_f32_16x16x32_bf16 v[64:67], v[172:175], v[206:209], v[64:67]
	s_setprio 0
	s_barrier
; #define PG8_STAGE(bufoff, gbase, voff) do { _Pragma("unroll") for (int _i = 0; _i < 2; ++_i) \
;         __builtin_amdgcn_global_load_lds((const unsigned*)((const char*)(gbase) + (voff)[_i]), (PG8_LAS unsigned*)(lds + (bufoff) + ldsw + _i * 8192), 16, 0, 0); } while (0)
; #define PG8_LDA(dst, b, h) do { _Pragma("unroll") for (int m = 0; m < 4; ++m) _Pragma("unroll") for (int k = 0; k < 2; ++k) dst[m][k] = *(const PG8_LAS bf16x8*)(lds + PG8_SA(b, h) + aoff + m * 2048 + k * 1024); } while (0)
; #define PG8_LDB(dst, b, h) do { _Pragma("unroll") for (int n = 0; n < 2; ++n) _Pragma("unroll") for (int k = 0; k < 2; ++k) dst[n][k] = *(const PG8_LAS bf16x8*)(lds + PG8_SB(b, h) + boff + n * 2048 + k * 1024); } while (0)
; #define PG8_MMA(ai, bj, At, Bt) do { __builtin_amdgcn_s_setprio(1); _Pragma("unroll") for (int m = 0; m < 4; ++m) _Pragma("unroll") for (int n = 0; n < 2; ++n) _Pragma("unroll") for (int k = 0; k < 2; ++k) \
;         acc[ai][bj][m][n] = __builtin_amdgcn_mfma_f32_16x16x32_bf16(Bt[n][k], At[m][k], acc[ai][bj][m][n], 0, 0, 0); __builtin_amdgcn_s_setprio(0); } while (0)
; #define PG8_WAIT_V(n) asm volatile("s_waitcnt vmcnt(" #n ")" ::: "memory")
; #define PG8_WAIT_L(n) asm volatile("s_waitcnt lgkmcnt(" #n ")" ::: "memory")
; #define PG8_BAR __builtin_amdgcn_s_barrier()
; #define PG8_SCHED __builtin_amdgcn_sched_barrier(0)
; template <class Epi, class Sched, bool ALIGN_EPI = false, bool SP2 = false>
; __device__ __forceinline__ void gemm_phase(PG8_LAS unsigned char* lds, const Gemm g, const Sched& S, const Epi& E) {
;     ...
;             PG8_LDA(At, 0, 1); PG8_STAGE(PG8_SB(0, 0), b2, voffB); PG8_STAGE(PG8_SB(0, 1), b2 + hstep, voffB); PG8_STAGE(PG8_SA(0, 0), a2, voffA);
;             PG8_WAIT_V(8); PG8_WAIT_L(0); PG8_BAR; PG8_MMA(1, 0, At, B0); PG8_MMA(1, 1, At, B1); PG8_BAR; PG8_SCHED;
;             PG8_LDB(B0, 1, 0); PG8_LDB(B1, 1, 1); PG8_SCHED; PG8_LDA(At, 1, 0); PG8_STAGE(PG8_SA(0, 1), a2 + hstep, voffA);
	s_add_i32 s33, s72, s3
	v_lshl_add_u64 v[210:211], s[78:79], 0, v[132:133]
	s_mov_b32 m0, s33
	ds_read_b128 v[176:179], v250 offset:16384
	ds_read_b128 v[180:183], v250 offset:17408
	ds_read_b128 v[184:187], v250 offset:18432
	ds_read_b128 v[188:191], v250 offset:19456
	ds_read_b128 v[194:197], v250 offset:20480
	ds_read_b128 v[198:201], v250 offset:21504
	ds_read_b128 v[202:205], v250 offset:22528
	ds_read_b128 v[206:209], v250 offset:23552
	global_load_lds_dwordx4 v[210:211], off
	s_add_i32 m0, s33, 0x2000
	v_lshl_add_u64 v[212:213], s[78:79], 0, v[136:137]
	s_add_u32 s78, s78, s16
	s_addc_u32 s79, s79, s17
	s_add_i32 s33, s73, s3
	global_load_lds_dwordx4 v[212:213], off
	v_lshl_add_u64 v[214:215], s[78:79], 0, v[132:133]
	s_mov_b32 m0, s33
	v_lshl_add_u64 v[216:217], s[78:79], 0, v[136:137]
	global_load_lds_dwordx4 v[214:215], off
	s_add_i32 m0, s33, 0x2000
	v_lshl_add_u64 v[218:219], s[60:61], 0, v[130:131]
	global_load_lds_dwordx4 v[216:217], off
	s_mov_b32 m0, s39
	v_lshl_add_u64 v[220:221], s[60:61], 0, v[134:135]
	global_load_lds_dwordx4 v[218:219], off
	s_mov_b32 m0, s49
	s_nop 0
	global_load_lds_dwordx4 v[220:221], off
	s_waitcnt vmcnt(8)
	s_waitcnt lgkmcnt(0)
	s_barrier
	s_setprio 1
	s_waitcnt lgkmcnt(0)
	v_mfma_f32_16x16x32_bf16 v[60:63], v[144:147], v[176:179], v[60:63]
	v_mfma_f32_16x16x32_bf16 v[56:59], v[152:155], v[176:179], v[56:59]
	v_mfma_f32_16x16x32_bf16 v[52:55], v[144:147], v[184:187], v[52:55]
	v_mfma_f32_16x16x32_bf16 v[48:51], v[152:155], v[184:187], v[48:51]
	v_mfma_f32_16x16x32_bf16 v[40:43], v[144:147], v[194:197], v[40:43]
	v_mfma_f32_16x16x32_bf16 v[32:35], v[152:155], v[194:197], v[32:35]
	v_mfma_f32_16x16x32_bf16 v[24:27], v[144:147], v[202:205], v[24:27]
	v_mfma_f32_16x16x32_bf16 v[16:19], v[152:155], v[202:205], v[16:19]
	v_mfma_f32_16x16x32_bf16 v[60:63], v[148:151], v[180:183], v[60:63]
	v_mfma_f32_16x16x32_bf16 v[56:59], v[156:159], v[180:183], v[56:59]
	v_mfma_f32_16x16x32_bf16 v[52:55], v[148:151], v[188:191], v[52:55]
	v_mfma_f32_16x16x32_bf16 v[48:51], v[156:159], v[188:191], v[48:51]
	v_mfma_f32_16x16x32_bf16 v[40:43], v[148:151], v[198:201], v[40:43]
	v_mfma_f32_16x16x32_bf16 v[32:35], v[156:159], v[198:201], v[32:35]
	v_mfma_f32_16x16x32_bf16 v[24:27], v[148:151], v[206:209], v[24:27]
	v_mfma_f32_16x16x32_bf16 v[16:19], v[156:159], v[206:209], v[16:19]
	s_setprio 0
	s_setprio 1
	v_mfma_f32_16x16x32_bf16 v[44:47], v[160:163], v[176:179], v[44:47]
	v_mfma_f32_16x16x32_bf16 v[36:39], v[168:171], v[176:179], v[36:39]
	v_mfma_f32_16x16x32_bf16 v[28:31], v[160:163], v[184:187], v[28:31]
	v_mfma_f32_16x16x32_bf16 v[20:23], v[168:171], v[184:187], v[20:23]
	v_mfma_f32_16x16x32_bf16 v[12:15], v[160:163], v[194:197], v[12:15]
	v_mfma_f32_16x16x32_bf16 v[8:11], v[168:171], v[194:197], v[8:11]
	v_mfma_f32_16x16x32_bf16 v[4:7], v[160:163], v[202:205], v[4:7]
	v_mfma_f32_16x16x32_bf16 v[0:3], v[168:171], v[202:205], v[0:3]
	v_mfma_f32_16x16x32_bf16 v[44:47], v[164:167], v[180:183], v[44:47]
	v_mfma_f32_16x16x32_bf16 v[36:39], v[172:175], v[180:183], v[36:39]
	v_mfma_f32_16x16x32_bf16 v[28:31], v[164:167], v[188:191], v[28:31]
	v_mfma_f32_16x16x32_bf16 v[20:23], v[172:175], v[188:191], v[20:23]
	v_mfma_f32_16x16x32_bf16 v[12:15], v[164:167], v[198:201], v[12:15]
	v_mfma_f32_16x16x32_bf16 v[8:11], v[172:175], v[198:201], v[8:11]
	v_mfma_f32_16x16x32_bf16 v[4:7], v[164:167], v[206:209], v[4:7]
	v_mfma_f32_16x16x32_bf16 v[0:3], v[172:175], v[206:209], v[0:3]
	s_setprio 0
	s_barrier
	s_add_i32 s33, 0, 0x18000
	v_add_u32_e32 v128, s33, v193
	s_add_i32 s77, 0, 0x1c000
	ds_read_b128 v[144:147], v128
	ds_read_b128 v[148:151], v128 offset:1024
	ds_read_b128 v[152:155], v128 offset:2048
	ds_read_b128 v[156:159], v128 offset:3072
	v_add_u32_e32 v128, s77, v193
	ds_read_b128 v[160:163], v128
	ds_read_b128 v[164:167], v128 offset:1024
	ds_read_b128 v[168:171], v128 offset:2048
	ds_read_b128 v[172:175], v128 offset:3072
	s_add_u32 s60, s60, s16
	s_addc_u32 s61, s61, s17
	s_mov_b32 m0, s62
	v_lshl_add_u64 v[222:223], s[60:61], 0, v[130:131]
	ds_read_b128 v[176:179], v250 offset:32768
	ds_read_b128 v[180:183], v250 offset:33792
	ds_read_b128 v[184:187], v250 offset:34816
	ds_read_b128 v[188:191], v250 offset:35840
	ds_read_b128 v[194:197], v250 offset:36864
	ds_read_b128 v[198:201], v250 offset:37888
	ds_read_b128 v[202:205], v250 offset:38912
	ds_read_b128 v[206:209], v250 offset:39936
	global_load_lds_dwordx4 v[222:223], off
	v_lshl_add_u64 v[222:223], s[60:61], 0, v[134:135]
	s_mov_b32 m0, s63
	s_nop 0
	global_load_lds_dwordx4 v[222:223], off
	s_waitcnt vmcnt(8)
	s_waitcnt lgkmcnt(0)
	s_barrier
; #define PG8_STAGE(bufoff, gbase, voff) do { _Pragma("unroll") for (int _i = 0; _i < 2; ++_i) \
;         __builtin_amdgcn_global_load_lds((const unsigned*)((const char*)(gbase) + (voff)[_i]), (PG8_LAS unsigned*)(lds + (bufoff) + ldsw + _i * 8192), 16, 0, 0); } while (0)
; #define PG8_LDA(dst, b, h) do { _Pragma("unroll") for (int m = 0; m < 4; ++m) _Pragma("unroll") for (int k = 0; k < 2; ++k) dst[m][k] = *(const PG8_LAS bf16x8*)(lds + PG8_SA(b, h) + aoff + m * 2048 + k * 1024); } while (0)
; #define PG8_MMA(ai, bj, At, Bt) do { __builtin_amdgcn_s_setprio(1); _Pragma("unroll") for (int m = 0; m < 4; ++m) _Pragma("unroll") for (int n = 0; n < 2; ++n) _Pragma("unroll") for (int k = 0; k < 2; ++k) \
;         acc[ai][bj][m][n] = __builtin_amdgcn_mfma_f32_16x16x32_bf16(Bt[n][k], At[m][k], acc[ai][bj][m][n], 0, 0, 0); __builtin_amdgcn_s_setprio(0); } while (0)
; #define PG8_WAIT_V(n) asm volatile("s_waitcnt vmcnt(" #n ")" ::: "memory")
; #define PG8_WAIT_L(n) asm volatile("s_waitcnt lgkmcnt(" #n ")" ::: "memory")
; #define PG8_BAR __builtin_amdgcn_s_barrier()
; #define PG8_SCHED __builtin_amdgcn_sched_barrier(0)
; template <class Epi, class Sched, bool ALIGN_EPI = false, bool SP2 = false>
; __device__ __forceinline__ void gemm_phase(PG8_LAS unsigned char* lds, const Gemm g, const Sched& S, const Epi& E) {
;     ...
;             PG8_WAIT_V(8); PG8_WAIT_L(0); PG8_BAR; PG8_MMA(0, 0, At, B0); PG8_MMA(0, 1, At, B1); PG8_BAR; PG8_SCHED;
;             PG8_LDA(At, 1, 1); PG8_STAGE(PG8_SB(1, 0), b3, voffB); PG8_STAGE(PG8_SB(1, 1), b3 + hstep, voffB); PG8_STAGE(PG8_SA(1, 0), a3, voffA);
;             PG8_WAIT_V(8); PG8_WAIT_L(0); PG8_BAR; PG8_MMA(1, 0, At, B0); PG8_MMA(1, 1, At, B1); PG8_BAR; PG8_SCHED;
	s_setprio 1
	s_waitcnt lgkmcnt(0)
	v_mfma_f32_16x16x32_bf16 v[124:127], v[144:147], v[176:179], v[124:127]
	v_mfma_f32_16x16x32_bf16 v[120:123], v[152:155], v[176:179], v[120:123]
	v_mfma_f32_16x16x32_bf16 v[116:119], v[144:147], v[184:187], v[116:119]
	v_mfma_f32_16x16x32_bf16 v[112:115], v[152:155], v[184:187], v[112:115]
	v_mfma_f32_16x16x32_bf16 v[104:107], v[144:147], v[194:197], v[104:107]
	v_mfma_f32_16x16x32_bf16 v[96:99], v[152:155], v[194:197], v[96:99]
	v_mfma_f32_16x16x32_bf16 v[88:91], v[144:147], v[202:205], v[88:91]
	v_mfma_f32_16x16x32_bf16 v[80:83], v[152:155], v[202:205], v[80:83]
	v_mfma_f32_16x16x32_bf16 v[124:127], v[148:151], v[180:183], v[124:127]
	v_mfma_f32_16x16x32_bf16 v[120:123], v[156:159], v[180:183], v[120:123]
	v_mfma_f32_16x16x32_bf16 v[116:119], v[148:151], v[188:191], v[116:119]
	v_mfma_f32_16x16x32_bf16 v[112:115], v[156:159], v[188:191], v[112:115]
	v_mfma_f32_16x16x32_bf16 v[104:107], v[148:151], v[198:201], v[104:107]
	v_mfma_f32_16x16x32_bf16 v[96:99], v[156:159], v[198:201], v[96:99]
	v_mfma_f32_16x16x32_bf16 v[88:91], v[148:151], v[206:209], v[88:91]
	v_mfma_f32_16x16x32_bf16 v[80:83], v[156:159], v[206:209], v[80:83]
	s_setprio 0
	s_setprio 1
	v_mfma_f32_16x16x32_bf16 v[108:111], v[160:163], v[176:179], v[108:111]
	v_mfma_f32_16x16x32_bf16 v[100:103], v[168:171], v[176:179], v[100:103]
	v_mfma_f32_16x16x32_bf16 v[92:95], v[160:163], v[184:187], v[92:95]
	v_mfma_f32_16x16x32_bf16 v[84:87], v[168:171], v[184:187], v[84:87]
	v_mfma_f32_16x16x32_bf16 v[76:79], v[160:163], v[194:197], v[76:79]
	v_mfma_f32_16x16x32_bf16 v[72:75], v[168:171], v[194:197], v[72:75]
	v_mfma_f32_16x16x32_bf16 v[68:71], v[160:163], v[202:205], v[68:71]
	v_mfma_f32_16x16x32_bf16 v[64:67], v[168:171], v[202:205], v[64:67]
	v_mfma_f32_16x16x32_bf16 v[108:111], v[164:167], v[180:183], v[108:111]
	v_mfma_f32_16x16x32_bf16 v[100:103], v[172:175], v[180:183], v[100:103]
	v_mfma_f32_16x16x32_bf16 v[92:95], v[164:167], v[188:191], v[92:95]
	v_mfma_f32_16x16x32_bf16 v[84:87], v[172:175], v[188:191], v[84:87]
	v_mfma_f32_16x16x32_bf16 v[76:79], v[164:167], v[198:201], v[76:79]
	v_mfma_f32_16x16x32_bf16 v[72:75], v[172:175], v[198:201], v[72:75]
	v_mfma_f32_16x16x32_bf16 v[68:71], v[164:167], v[206:209], v[68:71]
	v_mfma_f32_16x16x32_bf16 v[64:67], v[172:175], v[206:209], v[64:67]
	s_setprio 0
	s_barrier
	s_add_i32 s33, s33, s3
	v_lshl_add_u64 v[210:211], v[210:211], 0, s[36:37]
	s_mov_b32 m0, s33
	ds_read_b128 v[176:179], v250 offset:49152
	ds_read_b128 v[180:183], v250 offset:50176
	ds_read_b128 v[184:187], v250 offset:51200
	ds_read_b128 v[188:191], v250 offset:52224
	ds_read_b128 v[194:197], v250 offset:53248
	ds_read_b128 v[198:201], v250 offset:54272
	ds_read_b128 v[202:205], v250 offset:55296
	ds_read_b128 v[206:209], v250 offset:56320
	global_load_lds_dwordx4 v[210:211], off
	v_lshl_add_u64 v[210:211], v[212:213], 0, s[36:37]
	s_add_i32 m0, s33, 0x2000
	s_add_i32 s33, s77, s3
	global_load_lds_dwordx4 v[210:211], off
	v_lshl_add_u64 v[210:211], v[214:215], 0, s[36:37]
	s_mov_b32 m0, s33
	s_nop 0
	global_load_lds_dwordx4 v[210:211], off
	v_lshl_add_u64 v[210:211], v[216:217], 0, s[36:37]
	s_add_i32 m0, s33, 0x2000
	s_nop 0
	global_load_lds_dwordx4 v[210:211], off
	v_lshl_add_u64 v[210:211], v[218:219], 0, s[36:37]
	s_mov_b32 m0, s64
	s_nop 0
	global_load_lds_dwordx4 v[210:211], off
	v_lshl_add_u64 v[210:211], v[220:221], 0, s[36:37]
	s_mov_b32 m0, s65
	s_nop 0
	global_load_lds_dwordx4 v[210:211], off
	s_waitcnt vmcnt(8)
	s_waitcnt lgkmcnt(0)
	s_barrier
	s_setprio 1
	s_waitcnt lgkmcnt(0)
	v_mfma_f32_16x16x32_bf16 v[60:63], v[144:147], v[176:179], v[60:63]
	v_mfma_f32_16x16x32_bf16 v[56:59], v[152:155], v[176:179], v[56:59]
	v_mfma_f32_16x16x32_bf16 v[52:55], v[144:147], v[184:187], v[52:55]
	v_mfma_f32_16x16x32_bf16 v[48:51], v[152:155], v[184:187], v[48:51]
	v_mfma_f32_16x16x32_bf16 v[40:43], v[144:147], v[194:197], v[40:43]
	v_mfma_f32_16x16x32_bf16 v[32:35], v[152:155], v[194:197], v[32:35]
	v_mfma_f32_16x16x32_bf16 v[24:27], v[144:147], v[202:205], v[24:27]
	v_mfma_f32_16x16x32_bf16 v[16:19], v[152:155], v[202:205], v[16:19]
	v_mfma_f32_16x16x32_bf16 v[60:63], v[148:151], v[180:183], v[60:63]
	v_mfma_f32_16x16x32_bf16 v[56:59], v[156:159], v[180:183], v[56:59]
	v_mfma_f32_16x16x32_bf16 v[52:55], v[148:151], v[188:191], v[52:55]
	v_mfma_f32_16x16x32_bf16 v[48:51], v[156:159], v[188:191], v[48:51]
	v_mfma_f32_16x16x32_bf16 v[40:43], v[148:151], v[198:201], v[40:43]
	v_mfma_f32_16x16x32_bf16 v[32:35], v[156:159], v[198:201], v[32:35]
	v_mfma_f32_16x16x32_bf16 v[24:27], v[148:151], v[206:209], v[24:27]
	v_mfma_f32_16x16x32_bf16 v[16:19], v[156:159], v[206:209], v[16:19]
	s_setprio 0
	s_setprio 1
	v_mfma_f32_16x16x32_bf16 v[44:47], v[160:163], v[176:179], v[44:47]
	v_mfma_f32_16x16x32_bf16 v[36:39], v[168:171], v[176:179], v[36:39]
	v_mfma_f32_16x16x32_bf16 v[28:31], v[160:163], v[184:187], v[28:31]
	v_mfma_f32_16x16x32_bf16 v[20:23], v[168:171], v[184:187], v[20:23]
	v_mfma_f32_16x16x32_bf16 v[12:15], v[160:163], v[194:197], v[12:15]
	v_mfma_f32_16x16x32_bf16 v[8:11], v[168:171], v[194:197], v[8:11]
	v_mfma_f32_16x16x32_bf16 v[4:7], v[160:163], v[202:205], v[4:7]
	v_mfma_f32_16x16x32_bf16 v[0:3], v[168:171], v[202:205], v[0:3]
	v_mfma_f32_16x16x32_bf16 v[44:47], v[164:167], v[180:183], v[44:47]
	v_mfma_f32_16x16x32_bf16 v[36:39], v[172:175], v[180:183], v[36:39]
	v_mfma_f32_16x16x32_bf16 v[28:31], v[164:167], v[188:191], v[28:31]
	v_mfma_f32_16x16x32_bf16 v[20:23], v[172:175], v[188:191], v[20:23]
	v_mfma_f32_16x16x32_bf16 v[12:15], v[164:167], v[198:201], v[12:15]
	v_mfma_f32_16x16x32_bf16 v[8:11], v[172:175], v[198:201], v[8:11]
	v_mfma_f32_16x16x32_bf16 v[4:7], v[164:167], v[206:209], v[4:7]
	v_mfma_f32_16x16x32_bf16 v[0:3], v[172:175], v[206:209], v[0:3]
	s_setprio 0
	s_barrier
	s_add_u32 s58, s58, 0x100
	s_addc_u32 s59, s59, 0
	s_add_u32 s4, s4, 0x100
	s_addc_u32 s5, s5, 0
	s_cmp_ge_i32 s38, s67
	s_mov_b32 s33, s38
	s_cbranch_scc0 .LBB0_368
; __device__ __forceinline__ unsigned cvt_pk_bf16(float lo, float hi) { unsigned r; asm volatile("v_cvt_pk_bf16_f32 %0, %1, %2" : "=v"(r) : "v"(lo), "v"(hi)); return r; }
; #define PG8_BAR __builtin_amdgcn_s_barrier()
;     __device__ __forceinline__ void operator()(const f32x4 (&acc)[2][2][4][2], const Unit& u, int wr, int wc, int fr, int fq) const {
;         const int row0 = u.pm * BM + wr * 64 + fr, col0 = u.pn * BM + wc * 32 + 8 * fq;
;         u32x4 rb[2][4][2];
; #pragma unroll
;         for (int ai = 0; ai < 2; ++ai)
; #pragma unroll
;             for (int m = 0; m < 4; ++m) { const bf16_t* xq = XB + (size_t)(row0 + ai * HALF + m * 16) * 1024 + col0; rb[ai][m][0] = *(const u32x4*)xq; rb[ai][m][1] = *(const u32x4*)(xq + HALF); }
; #pragma unroll
;         for (int ai = 0; ai < 2; ++ai) {
; #pragma unroll
;             for (int m = 0; m < 4; ++m) {
;                 const int r = row0 + ai * HALF + m * 16;
;                 bf16_t* xp = XB + (size_t)r * 1024 + col0;
;                 const u32x4 b0 = rb[ai][m][0], b1 = rb[ai][m][1];
;                 float ss = 0.f;
; #pragma unroll
;                 for (int bj = 0; bj < 2; ++bj) {
;                     const u32x4 b = bj ? b1 : b0;
;                     f32x4 v0, v1;
;                     v0[0] = __uint_as_float(b.x << 16); v0[1] = __uint_as_float(b.x & 0xffff0000u); v0[2] = __uint_as_float(b.y << 16); v0[3] = __uint_as_float(b.y & 0xffff0000u);
;                     v1[0] = __uint_as_float(b.z << 16); v1[1] = __uint_as_float(b.z & 0xffff0000u); v1[2] = __uint_as_float(b.w << 16); v1[3] = __uint_as_float(b.w & 0xffff0000u);
;                     v0 += acc[ai][bj][m][0] * alpha; v1 += acc[ai][bj][m][1] * alpha;
;                     ss += (v0[0] * v0[0] + v0[1] * v0[1]) + (v0[2] * v0[2] + v0[3] * v0[3]) + (v1[0] * v1[0] + v1[1] * v1[1]) + (v1[2] * v1[2] + v1[3] * v1[3]);
;                     u32x4 w; w.x = cvt_pk_bf16(v0[0], v0[1]); w.y = cvt_pk_bf16(v0[2], v0[3]); w.z = cvt_pk_bf16(v1[0], v1[1]); w.w = cvt_pk_bf16(v1[2], v1[3]);
;                     *(u32x4*)(xp + bj * HALF) = w;
; template <class Epi, class Sched, bool ALIGN_EPI = false, bool SP2 = false>
; __device__ __forceinline__ void gemm_phase(PG8_LAS unsigned char* lds, const Gemm g, const Sched& S, const Epi& E) {
;     ...
;         if constexpr (ALIGN_EPI) { if (wr == 0) PG8_BAR; }
.LBB0_370:
	s_and_b64 vcc, exec, s[42:43]
	s_cbranch_vccz .LBB0_372
	s_barrier
.LBB0_372:
	v_lshl_or_b32 v144, s20, 8, v246
	v_lshl_add_u32 v146, s48, 8, v129
	v_lshlrev_b32_e32 v144, 1, v144
	v_mov_b32_e32 v145, 0
	v_mov_b32_e32 v147, 0
	s_mov_b32 s84, 0x8000
	s_mov_b32 s85, 0
	s_mov_b32 s86, 0x40000
	s_mov_b32 s87, 0
	v_lshl_add_u64 v[148:149], s[34:35], 0, v[144:145]
	v_lshlrev_b32_e32 v236, 11, v146
	v_mov_b32_e32 v237, 0
	v_lshl_add_u64 v[148:149], v[148:149], 0, v[236:237]
	v_lshl_add_u64 v[156:157], v[148:149], 0, s[86:87]
	v_lshl_add_u64 v[150:151], v[148:149], 0, s[84:85]
	v_lshl_add_u64 v[152:153], v[150:151], 0, s[84:85]
	v_lshl_add_u64 v[154:155], v[152:153], 0, s[84:85]
	v_lshl_add_u64 v[160:161], v[156:157], 0, s[84:85]
	v_lshl_add_u64 v[162:163], v[160:161], 0, s[84:85]
	v_lshl_add_u64 v[164:165], v[162:163], 0, s[84:85]
	global_load_dwordx4 v[168:171], v[148:149], off
	global_load_dwordx4 v[172:175], v[148:149], off offset:256
	global_load_dwordx4 v[176:179], v[150:151], off
	global_load_dwordx4 v[180:183], v[150:151], off offset:256
	global_load_dwordx4 v[184:187], v[152:153], off
	global_load_dwordx4 v[188:191], v[152:153], off offset:256
	global_load_dwordx4 v[196:199], v[154:155], off
	global_load_dwordx4 v[200:203], v[154:155], off offset:256
	global_load_dwordx4 v[204:207], v[156:157], off
	global_load_dwordx4 v[208:211], v[156:157], off offset:256
	global_load_dwordx4 v[212:215], v[160:161], off
	global_load_dwordx4 v[216:219], v[160:161], off offset:256
	global_load_dwordx4 v[220:223], v[162:163], off
	global_load_dwordx4 v[224:227], v[162:163], off offset:256
	global_load_dwordx4 v[228:231], v[164:165], off
	global_load_dwordx4 v[232:235], v[164:165], off offset:256
	v_xor_b32_e32 v128, 16, v247
	v_xor_b32_e32 v158, 32, v247
	v_lshlrev_b32_e32 v128, 2, v128
	v_lshlrev_b32_e32 v158, 2, v158
	s_lshl_b32 s90, s20, 2
	s_add_i32 s90, s90, s66
	s_lshl_b32 s90, s90, 2
	s_mov_b32 s91, 0
	v_lshlrev_b32_e32 v238, 6, v146
	v_mov_b32_e32 v239, 0
	v_lshl_add_u64 v[194:195], s[44:45], 0, v[238:239]
	v_lshl_add_u64 v[194:195], v[194:195], 0, s[90:91]
	s_waitcnt vmcnt(0)
	v_lshlrev_b32_e32 v236, 16, v168
	v_and_b32_e32 v237, 0xffff0000, v168
	v_lshlrev_b32_e32 v238, 16, v169
	v_and_b32_e32 v239, 0xffff0000, v169
	v_lshlrev_b32_e32 v240, 16, v170
	v_and_b32_e32 v241, 0xffff0000, v170
	v_lshlrev_b32_e32 v242, 16, v171
	v_and_b32_e32 v243, 0xffff0000, v171
	v_pk_fma_f32 v[124:125], v[124:125], 0.5, v[236:237] op_sel_hi:[1,0,1]
	v_pk_fma_f32 v[126:127], v[126:127], 0.5, v[238:239] op_sel_hi:[1,0,1]
	v_pk_fma_f32 v[120:121], v[120:121], 0.5, v[240:241] op_sel_hi:[1,0,1]
	v_pk_fma_f32 v[122:123], v[122:123], 0.5, v[242:243] op_sel_hi:[1,0,1]
	v_pk_mul_f32 v[166:167], v[124:125], v[124:125]
	v_pk_fma_f32 v[166:167], v[126:127], v[126:127], v[166:167]
	v_pk_fma_f32 v[166:167], v[120:121], v[120:121], v[166:167]
	v_pk_fma_f32 v[166:167], v[122:123], v[122:123], v[166:167]
	v_cvt_pk_bf16_f32 v168, v124, v125
	v_cvt_pk_bf16_f32 v169, v126, v127
	v_cvt_pk_bf16_f32 v170, v120, v121
	v_cvt_pk_bf16_f32 v171, v122, v123
	global_store_dwordx4 v[148:149], v[168:171], off
	v_lshlrev_b32_e32 v236, 16, v172
	v_and_b32_e32 v237, 0xffff0000, v172
	v_lshlrev_b32_e32 v238, 16, v173
	v_and_b32_e32 v239, 0xffff0000, v173
	v_lshlrev_b32_e32 v240, 16, v174
	v_and_b32_e32 v241, 0xffff0000, v174
	v_lshlrev_b32_e32 v242, 16, v175
	v_and_b32_e32 v243, 0xffff0000, v175
	v_pk_fma_f32 v[108:109], v[108:109], 0.5, v[236:237] op_sel_hi:[1,0,1]
	v_pk_fma_f32 v[110:111], v[110:111], 0.5, v[238:239] op_sel_hi:[1,0,1]
	v_pk_fma_f32 v[100:101], v[100:101], 0.5, v[240:241] op_sel_hi:[1,0,1]
	v_pk_fma_f32 v[102:103], v[102:103], 0.5, v[242:243] op_sel_hi:[1,0,1]
	v_pk_fma_f32 v[166:167], v[108:109], v[108:109], v[166:167]
	v_pk_fma_f32 v[166:167], v[110:111], v[110:111], v[166:167]
	v_pk_fma_f32 v[166:167], v[100:101], v[100:101], v[166:167]
	v_pk_fma_f32 v[166:167], v[102:103], v[102:103], v[166:167]
	v_cvt_pk_bf16_f32 v172, v108, v109
	v_cvt_pk_bf16_f32 v173, v110, v111
	v_cvt_pk_bf16_f32 v174, v100, v101
	v_cvt_pk_bf16_f32 v175, v102, v103
	global_store_dwordx4 v[148:149], v[172:175], off offset:256
	s_nop 0
	v_add_f32_e32 v148, v166, v167
	v_lshlrev_b32_e32 v236, 16, v176
	v_and_b32_e32 v237, 0xffff0000, v176
	v_lshlrev_b32_e32 v238, 16, v177
	v_and_b32_e32 v239, 0xffff0000, v177
	v_lshlrev_b32_e32 v240, 16, v178
	v_and_b32_e32 v241, 0xffff0000, v178
	v_lshlrev_b32_e32 v242, 16, v179
	v_and_b32_e32 v243, 0xffff0000, v179
	v_pk_fma_f32 v[116:117], v[116:117], 0.5, v[236:237] op_sel_hi:[1,0,1]
	v_pk_fma_f32 v[118:119], v[118:119], 0.5, v[238:239] op_sel_hi:[1,0,1]
	v_pk_fma_f32 v[112:113], v[112:113], 0.5, v[240:241] op_sel_hi:[1,0,1]
	v_pk_fma_f32 v[114:115], v[114:115], 0.5, v[242:243] op_sel_hi:[1,0,1]
	v_pk_mul_f32 v[166:167], v[116:117], v[116:117]
	v_pk_fma_f32 v[166:167], v[118:119], v[118:119], v[166:167]
	v_pk_fma_f32 v[166:167], v[112:113], v[112:113], v[166:167]
	v_pk_fma_f32 v[166:167], v[114:115], v[114:115], v[166:167]
	v_cvt_pk_bf16_f32 v176, v116, v117
	v_cvt_pk_bf16_f32 v177, v118, v119
	v_cvt_pk_bf16_f32 v178, v112, v113
	v_cvt_pk_bf16_f32 v179, v114, v115
	global_store_dwordx4 v[150:151], v[176:179], off
	v_lshlrev_b32_e32 v236, 16, v180
	v_and_b32_e32 v237, 0xffff0000, v180
	v_lshlrev_b32_e32 v238, 16, v181
	v_and_b32_e32 v239, 0xffff0000, v181
	v_lshlrev_b32_e32 v240, 16, v182
	v_and_b32_e32 v241, 0xffff0000, v182
	v_lshlrev_b32_e32 v242, 16, v183
	v_and_b32_e32 v243, 0xffff0000, v183
	v_pk_fma_f32 v[92:93], v[92:93], 0.5, v[236:237] op_sel_hi:[1,0,1]
	v_pk_fma_f32 v[94:95], v[94:95], 0.5, v[238:239] op_sel_hi:[1,0,1]
; __device__ __forceinline__ unsigned cvt_pk_bf16(float lo, float hi) { unsigned r; asm volatile("v_cvt_pk_bf16_f32 %0, %1, %2" : "=v"(r) : "v"(lo), "v"(hi)); return r; }
; __device__ __forceinline__ unsigned cvt_pk_bf16(float lo, float hi) { const f32x2 v = {lo, hi}; const bf16x2_t b = __builtin_convertvector(v, bf16x2_t); return __builtin_bit_cast(unsigned, b); }
;     __device__ __forceinline__ void operator()(const f32x4 (&acc)[2][2][4][2], const Unit& u, int wr, int wc, int fr, int fq) const {
;     ...
;                 const u32x4 b0 = rb[ai][m][0], b1 = rb[ai][m][1];
;                 float ss = 0.f;
; #pragma unroll
;                 for (int bj = 0; bj < 2; ++bj) {
;                     const u32x4 b = bj ? b1 : b0;
;                     f32x4 v0, v1;
;                     v0[0] = __uint_as_float(b.x << 16); v0[1] = __uint_as_float(b.x & 0xffff0000u); v0[2] = __uint_as_float(b.y << 16); v0[3] = __uint_as_float(b.y & 0xffff0000u);
;                     v1[0] = __uint_as_float(b.z << 16); v1[1] = __uint_as_float(b.z & 0xffff0000u); v1[2] = __uint_as_float(b.w << 16); v1[3] = __uint_as_float(b.w & 0xffff0000u);
;                     v0 += acc[ai][bj][m][0] * alpha; v1 += acc[ai][bj][m][1] * alpha;
;                     ss += (v0[0] * v0[0] + v0[1] * v0[1]) + (v0[2] * v0[2] + v0[3] * v0[3]) + (v1[0] * v1[0] + v1[1] * v1[1]) + (v1[2] * v1[2] + v1[3] * v1[3]);
;                     u32x4 w; w.x = cvt_pk_bf16(v0[0], v0[1]); w.y = cvt_pk_bf16(v0[2], v0[3]); w.z = cvt_pk_bf16(v1[0], v1[1]); w.w = cvt_pk_bf16(v1[2], v1[3]);
;                     *(u32x4*)(xp + bj * HALF) = w;
	v_pk_fma_f32 v[84:85], v[84:85], 0.5, v[240:241] op_sel_hi:[1,0,1]
	v_pk_fma_f32 v[86:87], v[86:87], 0.5, v[242:243] op_sel_hi:[1,0,1]
	v_pk_fma_f32 v[166:167], v[92:93], v[92:93], v[166:167]
	v_pk_fma_f32 v[166:167], v[94:95], v[94:95], v[166:167]
	v_pk_fma_f32 v[166:167], v[84:85], v[84:85], v[166:167]
	v_pk_fma_f32 v[166:167], v[86:87], v[86:87], v[166:167]
	v_cvt_pk_bf16_f32 v180, v92, v93
	v_cvt_pk_bf16_f32 v181, v94, v95
	v_cvt_pk_bf16_f32 v182, v84, v85
	v_cvt_pk_bf16_f32 v183, v86, v87
	global_store_dwordx4 v[150:151], v[180:183], off offset:256
	s_nop 0
	v_add_f32_e32 v150, v166, v167
	v_lshlrev_b32_e32 v236, 16, v184
	v_and_b32_e32 v237, 0xffff0000, v184
	v_lshlrev_b32_e32 v238, 16, v185
	v_and_b32_e32 v239, 0xffff0000, v185
	v_lshlrev_b32_e32 v240, 16, v186
	v_and_b32_e32 v241, 0xffff0000, v186
	v_lshlrev_b32_e32 v242, 16, v187
	v_and_b32_e32 v243, 0xffff0000, v187
	v_pk_fma_f32 v[104:105], v[104:105], 0.5, v[236:237] op_sel_hi:[1,0,1]
	v_pk_fma_f32 v[106:107], v[106:107], 0.5, v[238:239] op_sel_hi:[1,0,1]
	v_pk_fma_f32 v[96:97], v[96:97], 0.5, v[240:241] op_sel_hi:[1,0,1]
	v_pk_fma_f32 v[98:99], v[98:99], 0.5, v[242:243] op_sel_hi:[1,0,1]
	v_pk_mul_f32 v[166:167], v[104:105], v[104:105]
	v_pk_fma_f32 v[166:167], v[106:107], v[106:107], v[166:167]
	v_pk_fma_f32 v[166:167], v[96:97], v[96:97], v[166:167]
	v_pk_fma_f32 v[166:167], v[98:99], v[98:99], v[166:167]
	v_cvt_pk_bf16_f32 v184, v104, v105
	v_cvt_pk_bf16_f32 v185, v106, v107
	v_cvt_pk_bf16_f32 v186, v96, v97
	v_cvt_pk_bf16_f32 v187, v98, v99
	global_store_dwordx4 v[152:153], v[184:187], off
	v_lshlrev_b32_e32 v236, 16, v188
	v_and_b32_e32 v237, 0xffff0000, v188
	v_lshlrev_b32_e32 v238, 16, v189
	v_and_b32_e32 v239, 0xffff0000, v189
	v_lshlrev_b32_e32 v240, 16, v190
	v_and_b32_e32 v241, 0xffff0000, v190
	v_lshlrev_b32_e32 v242, 16, v191
	v_and_b32_e32 v243, 0xffff0000, v191
	v_pk_fma_f32 v[76:77], v[76:77], 0.5, v[236:237] op_sel_hi:[1,0,1]
	v_pk_fma_f32 v[78:79], v[78:79], 0.5, v[238:239] op_sel_hi:[1,0,1]
	v_pk_fma_f32 v[72:73], v[72:73], 0.5, v[240:241] op_sel_hi:[1,0,1]
	v_pk_fma_f32 v[74:75], v[74:75], 0.5, v[242:243] op_sel_hi:[1,0,1]
	v_pk_fma_f32 v[166:167], v[76:77], v[76:77], v[166:167]
	v_pk_fma_f32 v[166:167], v[78:79], v[78:79], v[166:167]
	v_pk_fma_f32 v[166:167], v[72:73], v[72:73], v[166:167]
	v_pk_fma_f32 v[166:167], v[74:75], v[74:75], v[166:167]
	v_cvt_pk_bf16_f32 v188, v76, v77
	v_cvt_pk_bf16_f32 v189, v78, v79
	v_cvt_pk_bf16_f32 v190, v72, v73
	v_cvt_pk_bf16_f32 v191, v74, v75
	global_store_dwordx4 v[152:153], v[188:191], off offset:256
	s_nop 0
	v_add_f32_e32 v152, v166, v167
	v_lshlrev_b32_e32 v236, 16, v196
	v_and_b32_e32 v237, 0xffff0000, v196
	v_lshlrev_b32_e32 v238, 16, v197
	v_and_b32_e32 v239, 0xffff0000, v197
	v_lshlrev_b32_e32 v240, 16, v198
	v_and_b32_e32 v241, 0xffff0000, v198
	v_lshlrev_b32_e32 v242, 16, v199
	v_and_b32_e32 v243, 0xffff0000, v199
	v_pk_fma_f32 v[88:89], v[88:89], 0.5, v[236:237] op_sel_hi:[1,0,1]
	v_pk_fma_f32 v[90:91], v[90:91], 0.5, v[238:239] op_sel_hi:[1,0,1]
	v_pk_fma_f32 v[80:81], v[80:81], 0.5, v[240:241] op_sel_hi:[1,0,1]
	v_pk_fma_f32 v[82:83], v[82:83], 0.5, v[242:243] op_sel_hi:[1,0,1]
	v_pk_mul_f32 v[166:167], v[88:89], v[88:89]
	v_pk_fma_f32 v[166:167], v[90:91], v[90:91], v[166:167]
	v_pk_fma_f32 v[166:167], v[80:81], v[80:81], v[166:167]
	v_pk_fma_f32 v[166:167], v[82:83], v[82:83], v[166:167]
	v_cvt_pk_bf16_f32 v196, v88, v89
	v_cvt_pk_bf16_f32 v197, v90, v91
	v_cvt_pk_bf16_f32 v198, v80, v81
	v_cvt_pk_bf16_f32 v199, v82, v83
	global_store_dwordx4 v[154:155], v[196:199], off
	v_lshlrev_b32_e32 v236, 16, v200
	v_and_b32_e32 v237, 0xffff0000, v200
	v_lshlrev_b32_e32 v238, 16, v201
	v_and_b32_e32 v239, 0xffff0000, v201
	v_lshlrev_b32_e32 v240, 16, v202
	v_and_b32_e32 v241, 0xffff0000, v202
	v_lshlrev_b32_e32 v242, 16, v203
	v_and_b32_e32 v243, 0xffff0000, v203
	v_pk_fma_f32 v[68:69], v[68:69], 0.5, v[236:237] op_sel_hi:[1,0,1]
	v_pk_fma_f32 v[70:71], v[70:71], 0.5, v[238:239] op_sel_hi:[1,0,1]
	v_pk_fma_f32 v[64:65], v[64:65], 0.5, v[240:241] op_sel_hi:[1,0,1]
	v_pk_fma_f32 v[66:67], v[66:67], 0.5, v[242:243] op_sel_hi:[1,0,1]
	v_pk_fma_f32 v[166:167], v[68:69], v[68:69], v[166:167]
	v_pk_fma_f32 v[166:167], v[70:71], v[70:71], v[166:167]
	v_pk_fma_f32 v[166:167], v[64:65], v[64:65], v[166:167]
	v_pk_fma_f32 v[166:167], v[66:67], v[66:67], v[166:167]
	v_cvt_pk_bf16_f32 v200, v68, v69
	v_cvt_pk_bf16_f32 v201, v70, v71
	v_cvt_pk_bf16_f32 v202, v64, v65
	v_cvt_pk_bf16_f32 v203, v66, v67
	global_store_dwordx4 v[154:155], v[200:203], off offset:256
	s_nop 0
	v_add_f32_e32 v154, v166, v167
	v_lshlrev_b32_e32 v236, 16, v204
	v_and_b32_e32 v237, 0xffff0000, v204
	v_lshlrev_b32_e32 v238, 16, v205
	v_and_b32_e32 v239, 0xffff0000, v205
	v_lshlrev_b32_e32 v240, 16, v206
	v_and_b32_e32 v241, 0xffff0000, v206
	v_lshlrev_b32_e32 v242, 16, v207
	v_and_b32_e32 v243, 0xffff0000, v207
	v_pk_fma_f32 v[60:61], v[60:61], 0.5, v[236:237] op_sel_hi:[1,0,1]
	v_pk_fma_f32 v[62:63], v[62:63], 0.5, v[238:239] op_sel_hi:[1,0,1]
	v_pk_fma_f32 v[56:57], v[56:57], 0.5, v[240:241] op_sel_hi:[1,0,1]
	v_pk_fma_f32 v[58:59], v[58:59], 0.5, v[242:243] op_sel_hi:[1,0,1]
	v_pk_mul_f32 v[166:167], v[60:61], v[60:61]
	v_pk_fma_f32 v[166:167], v[62:63], v[62:63], v[166:167]
	v_pk_fma_f32 v[166:167], v[56:57], v[56:57], v[166:167]
	v_pk_fma_f32 v[166:167], v[58:59], v[58:59], v[166:167]
	v_cvt_pk_bf16_f32 v204, v60, v61
	v_cvt_pk_bf16_f32 v205, v62, v63
	v_cvt_pk_bf16_f32 v206, v56, v57
	v_cvt_pk_bf16_f32 v207, v58, v59
	global_store_dwordx4 v[156:157], v[204:207], off
	v_lshlrev_b32_e32 v236, 16, v208
	v_and_b32_e32 v237, 0xffff0000, v208
; __device__ __forceinline__ unsigned cvt_pk_bf16(float lo, float hi) { unsigned r; asm volatile("v_cvt_pk_bf16_f32 %0, %1, %2" : "=v"(r) : "v"(lo), "v"(hi)); return r; }
; __device__ __forceinline__ unsigned cvt_pk_bf16(float lo, float hi) { const f32x2 v = {lo, hi}; const bf16x2_t b = __builtin_convertvector(v, bf16x2_t); return __builtin_bit_cast(unsigned, b); }
;     __device__ __forceinline__ void operator()(const f32x4 (&acc)[2][2][4][2], const Unit& u, int wr, int wc, int fr, int fq) const {
;     ...
;                 const u32x4 b0 = rb[ai][m][0], b1 = rb[ai][m][1];
;                 float ss = 0.f;
; #pragma unroll
;                 for (int bj = 0; bj < 2; ++bj) {
;                     const u32x4 b = bj ? b1 : b0;
;                     f32x4 v0, v1;
;                     v0[0] = __uint_as_float(b.x << 16); v0[1] = __uint_as_float(b.x & 0xffff0000u); v0[2] = __uint_as_float(b.y << 16); v0[3] = __uint_as_float(b.y & 0xffff0000u);
;                     v1[0] = __uint_as_float(b.z << 16); v1[1] = __uint_as_float(b.z & 0xffff0000u); v1[2] = __uint_as_float(b.w << 16); v1[3] = __uint_as_float(b.w & 0xffff0000u);
;                     v0 += acc[ai][bj][m][0] * alpha; v1 += acc[ai][bj][m][1] * alpha;
;                     ss += (v0[0] * v0[0] + v0[1] * v0[1]) + (v0[2] * v0[2] + v0[3] * v0[3]) + (v1[0] * v1[0] + v1[1] * v1[1]) + (v1[2] * v1[2] + v1[3] * v1[3]);
;                     u32x4 w; w.x = cvt_pk_bf16(v0[0], v0[1]); w.y = cvt_pk_bf16(v0[2], v0[3]); w.z = cvt_pk_bf16(v1[0], v1[1]); w.w = cvt_pk_bf16(v1[2], v1[3]);
;                     *(u32x4*)(xp + bj * HALF) = w;
	v_lshlrev_b32_e32 v238, 16, v209
	v_and_b32_e32 v239, 0xffff0000, v209
	v_lshlrev_b32_e32 v240, 16, v210
	v_and_b32_e32 v241, 0xffff0000, v210
	v_lshlrev_b32_e32 v242, 16, v211
	v_and_b32_e32 v243, 0xffff0000, v211
	v_pk_fma_f32 v[44:45], v[44:45], 0.5, v[236:237] op_sel_hi:[1,0,1]
	v_pk_fma_f32 v[46:47], v[46:47], 0.5, v[238:239] op_sel_hi:[1,0,1]
	v_pk_fma_f32 v[36:37], v[36:37], 0.5, v[240:241] op_sel_hi:[1,0,1]
	v_pk_fma_f32 v[38:39], v[38:39], 0.5, v[242:243] op_sel_hi:[1,0,1]
	v_pk_fma_f32 v[166:167], v[44:45], v[44:45], v[166:167]
	v_pk_fma_f32 v[166:167], v[46:47], v[46:47], v[166:167]
	v_pk_fma_f32 v[166:167], v[36:37], v[36:37], v[166:167]
	v_pk_fma_f32 v[166:167], v[38:39], v[38:39], v[166:167]
	v_cvt_pk_bf16_f32 v208, v44, v45
	v_cvt_pk_bf16_f32 v209, v46, v47
	v_cvt_pk_bf16_f32 v210, v36, v37
	v_cvt_pk_bf16_f32 v211, v38, v39
	global_store_dwordx4 v[156:157], v[208:211], off offset:256
	s_nop 0
	v_add_f32_e32 v156, v166, v167
	v_lshlrev_b32_e32 v236, 16, v212
	v_and_b32_e32 v237, 0xffff0000, v212
	v_lshlrev_b32_e32 v238, 16, v213
	v_and_b32_e32 v239, 0xffff0000, v213
	v_lshlrev_b32_e32 v240, 16, v214
	v_and_b32_e32 v241, 0xffff0000, v214
	v_lshlrev_b32_e32 v242, 16, v215
	v_and_b32_e32 v243, 0xffff0000, v215
	v_pk_fma_f32 v[52:53], v[52:53], 0.5, v[236:237] op_sel_hi:[1,0,1]
	v_pk_fma_f32 v[54:55], v[54:55], 0.5, v[238:239] op_sel_hi:[1,0,1]
	v_pk_fma_f32 v[48:49], v[48:49], 0.5, v[240:241] op_sel_hi:[1,0,1]
	v_pk_fma_f32 v[50:51], v[50:51], 0.5, v[242:243] op_sel_hi:[1,0,1]
	v_pk_mul_f32 v[166:167], v[52:53], v[52:53]
	v_pk_fma_f32 v[166:167], v[54:55], v[54:55], v[166:167]
	v_pk_fma_f32 v[166:167], v[48:49], v[48:49], v[166:167]
	v_pk_fma_f32 v[166:167], v[50:51], v[50:51], v[166:167]
	v_cvt_pk_bf16_f32 v212, v52, v53
	v_cvt_pk_bf16_f32 v213, v54, v55
	v_cvt_pk_bf16_f32 v214, v48, v49
	v_cvt_pk_bf16_f32 v215, v50, v51
	global_store_dwordx4 v[160:161], v[212:215], off
	v_lshlrev_b32_e32 v236, 16, v216
	v_and_b32_e32 v237, 0xffff0000, v216
	v_lshlrev_b32_e32 v238, 16, v217
	v_and_b32_e32 v239, 0xffff0000, v217
	v_lshlrev_b32_e32 v240, 16, v218
	v_and_b32_e32 v241, 0xffff0000, v218
	v_lshlrev_b32_e32 v242, 16, v219
	v_and_b32_e32 v243, 0xffff0000, v219
	v_pk_fma_f32 v[28:29], v[28:29], 0.5, v[236:237] op_sel_hi:[1,0,1]
	v_pk_fma_f32 v[30:31], v[30:31], 0.5, v[238:239] op_sel_hi:[1,0,1]
	v_pk_fma_f32 v[20:21], v[20:21], 0.5, v[240:241] op_sel_hi:[1,0,1]
	v_pk_fma_f32 v[22:23], v[22:23], 0.5, v[242:243] op_sel_hi:[1,0,1]
	v_pk_fma_f32 v[166:167], v[28:29], v[28:29], v[166:167]
	v_pk_fma_f32 v[166:167], v[30:31], v[30:31], v[166:167]
	v_pk_fma_f32 v[166:167], v[20:21], v[20:21], v[166:167]
	v_pk_fma_f32 v[166:167], v[22:23], v[22:23], v[166:167]
	v_cvt_pk_bf16_f32 v216, v28, v29
	v_cvt_pk_bf16_f32 v217, v30, v31
	v_cvt_pk_bf16_f32 v218, v20, v21
	v_cvt_pk_bf16_f32 v219, v22, v23
	global_store_dwordx4 v[160:161], v[216:219], off offset:256
	s_nop 0
	v_add_f32_e32 v160, v166, v167
	v_lshlrev_b32_e32 v236, 16, v220
	v_and_b32_e32 v237, 0xffff0000, v220
	v_lshlrev_b32_e32 v238, 16, v221
	v_and_b32_e32 v239, 0xffff0000, v221
	v_lshlrev_b32_e32 v240, 16, v222
	v_and_b32_e32 v241, 0xffff0000, v222
	v_lshlrev_b32_e32 v242, 16, v223
	v_and_b32_e32 v243, 0xffff0000, v223
	v_pk_fma_f32 v[40:41], v[40:41], 0.5, v[236:237] op_sel_hi:[1,0,1]
	v_pk_fma_f32 v[42:43], v[42:43], 0.5, v[238:239] op_sel_hi:[1,0,1]
	v_pk_fma_f32 v[32:33], v[32:33], 0.5, v[240:241] op_sel_hi:[1,0,1]
	v_pk_fma_f32 v[34:35], v[34:35], 0.5, v[242:243] op_sel_hi:[1,0,1]
	v_pk_mul_f32 v[166:167], v[40:41], v[40:41]
	v_pk_fma_f32 v[166:167], v[42:43], v[42:43], v[166:167]
	v_pk_fma_f32 v[166:167], v[32:33], v[32:33], v[166:167]
	v_pk_fma_f32 v[166:167], v[34:35], v[34:35], v[166:167]
	v_cvt_pk_bf16_f32 v220, v40, v41
	v_cvt_pk_bf16_f32 v221, v42, v43
	v_cvt_pk_bf16_f32 v222, v32, v33
	v_cvt_pk_bf16_f32 v223, v34, v35
	global_store_dwordx4 v[162:163], v[220:223], off
	v_lshlrev_b32_e32 v236, 16, v224
	v_and_b32_e32 v237, 0xffff0000, v224
	v_lshlrev_b32_e32 v238, 16, v225
	v_and_b32_e32 v239, 0xffff0000, v225
	v_lshlrev_b32_e32 v240, 16, v226
	v_and_b32_e32 v241, 0xffff0000, v226
	v_lshlrev_b32_e32 v242, 16, v227
	v_and_b32_e32 v243, 0xffff0000, v227
	v_pk_fma_f32 v[12:13], v[12:13], 0.5, v[236:237] op_sel_hi:[1,0,1]
	v_pk_fma_f32 v[14:15], v[14:15], 0.5, v[238:239] op_sel_hi:[1,0,1]
	v_pk_fma_f32 v[8:9], v[8:9], 0.5, v[240:241] op_sel_hi:[1,0,1]
	v_pk_fma_f32 v[10:11], v[10:11], 0.5, v[242:243] op_sel_hi:[1,0,1]
	v_pk_fma_f32 v[166:167], v[12:13], v[12:13], v[166:167]
; __device__ __forceinline__ unsigned cvt_pk_bf16(float lo, float hi) { unsigned r; asm volatile("v_cvt_pk_bf16_f32 %0, %1, %2" : "=v"(r) : "v"(lo), "v"(hi)); return r; }
; __device__ __forceinline__ unsigned cvt_pk_bf16(float lo, float hi) { const f32x2 v = {lo, hi}; const bf16x2_t b = __builtin_convertvector(v, bf16x2_t); return __builtin_bit_cast(unsigned, b); }
;     __device__ __forceinline__ void operator()(const f32x4 (&acc)[2][2][4][2], const Unit& u, int wr, int wc, int fr, int fq) const {
;     ...
;                 const u32x4 b0 = rb[ai][m][0], b1 = rb[ai][m][1];
;                 float ss = 0.f;
; #pragma unroll
;                 for (int bj = 0; bj < 2; ++bj) {
;                     const u32x4 b = bj ? b1 : b0;
;                     f32x4 v0, v1;
;                     v0[0] = __uint_as_float(b.x << 16); v0[1] = __uint_as_float(b.x & 0xffff0000u); v0[2] = __uint_as_float(b.y << 16); v0[3] = __uint_as_float(b.y & 0xffff0000u);
;                     v1[0] = __uint_as_float(b.z << 16); v1[1] = __uint_as_float(b.z & 0xffff0000u); v1[2] = __uint_as_float(b.w << 16); v1[3] = __uint_as_float(b.w & 0xffff0000u);
;                     v0 += acc[ai][bj][m][0] * alpha; v1 += acc[ai][bj][m][1] * alpha;
;                     ss += (v0[0] * v0[0] + v0[1] * v0[1]) + (v0[2] * v0[2] + v0[3] * v0[3]) + (v1[0] * v1[0] + v1[1] * v1[1]) + (v1[2] * v1[2] + v1[3] * v1[3]);
;                     u32x4 w; w.x = cvt_pk_bf16(v0[0], v0[1]); w.y = cvt_pk_bf16(v0[2], v0[3]); w.z = cvt_pk_bf16(v1[0], v1[1]); w.w = cvt_pk_bf16(v1[2], v1[3]);
;                     *(u32x4*)(xp + bj * HALF) = w;
;                 }
;                 ss += __shfl_xor(ss, 16); ss += __shfl_xor(ss, 32);
;                 if (fq == 0) SS[(size_t)r * 16 + u.pn * 4 + wc] = ss;
	v_pk_fma_f32 v[166:167], v[14:15], v[14:15], v[166:167]
	v_pk_fma_f32 v[166:167], v[8:9], v[8:9], v[166:167]
	v_pk_fma_f32 v[166:167], v[10:11], v[10:11], v[166:167]
	v_cvt_pk_bf16_f32 v224, v12, v13
	v_cvt_pk_bf16_f32 v225, v14, v15
	v_cvt_pk_bf16_f32 v226, v8, v9
	v_cvt_pk_bf16_f32 v227, v10, v11
	global_store_dwordx4 v[162:163], v[224:227], off offset:256
	s_nop 0
	v_add_f32_e32 v162, v166, v167
	v_lshlrev_b32_e32 v236, 16, v228
	v_and_b32_e32 v237, 0xffff0000, v228
	v_lshlrev_b32_e32 v238, 16, v229
	v_and_b32_e32 v239, 0xffff0000, v229
	v_lshlrev_b32_e32 v240, 16, v230
	v_and_b32_e32 v241, 0xffff0000, v230
	v_lshlrev_b32_e32 v242, 16, v231
	v_and_b32_e32 v243, 0xffff0000, v231
	v_pk_fma_f32 v[24:25], v[24:25], 0.5, v[236:237] op_sel_hi:[1,0,1]
	v_pk_fma_f32 v[26:27], v[26:27], 0.5, v[238:239] op_sel_hi:[1,0,1]
	v_pk_fma_f32 v[16:17], v[16:17], 0.5, v[240:241] op_sel_hi:[1,0,1]
	v_pk_fma_f32 v[18:19], v[18:19], 0.5, v[242:243] op_sel_hi:[1,0,1]
	v_pk_mul_f32 v[166:167], v[24:25], v[24:25]
	v_pk_fma_f32 v[166:167], v[26:27], v[26:27], v[166:167]
	v_pk_fma_f32 v[166:167], v[16:17], v[16:17], v[166:167]
	v_pk_fma_f32 v[166:167], v[18:19], v[18:19], v[166:167]
	v_cvt_pk_bf16_f32 v228, v24, v25
	v_cvt_pk_bf16_f32 v229, v26, v27
	v_cvt_pk_bf16_f32 v230, v16, v17
	v_cvt_pk_bf16_f32 v231, v18, v19
	global_store_dwordx4 v[164:165], v[228:231], off
	v_lshlrev_b32_e32 v236, 16, v232
	v_and_b32_e32 v237, 0xffff0000, v232
	v_lshlrev_b32_e32 v238, 16, v233
	v_and_b32_e32 v239, 0xffff0000, v233
	v_lshlrev_b32_e32 v240, 16, v234
	v_and_b32_e32 v241, 0xffff0000, v234
	v_lshlrev_b32_e32 v242, 16, v235
	v_and_b32_e32 v243, 0xffff0000, v235
	v_pk_fma_f32 v[4:5], v[4:5], 0.5, v[236:237] op_sel_hi:[1,0,1]
	v_pk_fma_f32 v[6:7], v[6:7], 0.5, v[238:239] op_sel_hi:[1,0,1]
	v_pk_fma_f32 v[0:1], v[0:1], 0.5, v[240:241] op_sel_hi:[1,0,1]
	v_pk_fma_f32 v[2:3], v[2:3], 0.5, v[242:243] op_sel_hi:[1,0,1]
	v_pk_fma_f32 v[166:167], v[4:5], v[4:5], v[166:167]
	v_pk_fma_f32 v[166:167], v[6:7], v[6:7], v[166:167]
	v_pk_fma_f32 v[166:167], v[0:1], v[0:1], v[166:167]
	v_pk_fma_f32 v[166:167], v[2:3], v[2:3], v[166:167]
	v_cvt_pk_bf16_f32 v232, v4, v5
	v_cvt_pk_bf16_f32 v233, v6, v7
	v_cvt_pk_bf16_f32 v234, v0, v1
	v_cvt_pk_bf16_f32 v235, v2, v3
	global_store_dwordx4 v[164:165], v[232:235], off offset:256
	s_nop 0
	v_add_f32_e32 v164, v166, v167
	ds_bpermute_b32 v149, v128, v148
	ds_bpermute_b32 v151, v128, v150
	ds_bpermute_b32 v153, v128, v152
	ds_bpermute_b32 v155, v128, v154
	ds_bpermute_b32 v157, v128, v156
	ds_bpermute_b32 v161, v128, v160
	ds_bpermute_b32 v163, v128, v162
	ds_bpermute_b32 v165, v128, v164
	s_waitcnt lgkmcnt(7)
	v_add_f32_e32 v148, v148, v149
	s_waitcnt lgkmcnt(6)
	v_add_f32_e32 v150, v150, v151
	s_waitcnt lgkmcnt(5)
	v_add_f32_e32 v152, v152, v153
	s_waitcnt lgkmcnt(4)
	v_add_f32_e32 v154, v154, v155
	s_waitcnt lgkmcnt(3)
	v_add_f32_e32 v156, v156, v157
	s_waitcnt lgkmcnt(2)
	v_add_f32_e32 v160, v160, v161
	s_waitcnt lgkmcnt(1)
	v_add_f32_e32 v162, v162, v163
	s_waitcnt lgkmcnt(0)
	v_add_f32_e32 v164, v164, v165
	ds_bpermute_b32 v149, v158, v148
	ds_bpermute_b32 v151, v158, v150
	ds_bpermute_b32 v153, v158, v152
	ds_bpermute_b32 v155, v158, v154
	ds_bpermute_b32 v157, v158, v156
	ds_bpermute_b32 v161, v158, v160
	ds_bpermute_b32 v163, v158, v162
	ds_bpermute_b32 v165, v158, v164
	s_waitcnt lgkmcnt(7)
	v_add_f32_e32 v148, v148, v149
	s_waitcnt lgkmcnt(6)
	v_add_f32_e32 v150, v150, v151
	s_waitcnt lgkmcnt(5)
	v_add_f32_e32 v152, v152, v153
	s_waitcnt lgkmcnt(4)
	v_add_f32_e32 v154, v154, v155
	s_waitcnt lgkmcnt(3)
	v_add_f32_e32 v156, v156, v157
	s_waitcnt lgkmcnt(2)
	v_add_f32_e32 v160, v160, v161
	s_waitcnt lgkmcnt(1)
	v_add_f32_e32 v162, v162, v163
	s_waitcnt lgkmcnt(0)
	v_add_f32_e32 v164, v164, v165
	s_and_saveexec_b64 s[88:89], s[6:7]
	global_store_dword v[194:195], v148, off
	global_store_dword v[194:195], v150, off offset:1024
	global_store_dword v[194:195], v152, off offset:2048
	global_store_dword v[194:195], v154, off offset:3072
	s_movk_i32 s84, 0x2000
	v_lshl_add_u64 v[194:195], v[194:195], 0, s[84:85]
	global_store_dword v[194:195], v156, off
	global_store_dword v[194:195], v160, off offset:1024
	global_store_dword v[194:195], v162, off offset:2048
	global_store_dword v[194:195], v164, off offset:3072
	s_or_b64 exec, exec, s[88:89]
	v_and_b32_e32 v56, 64, v247
	v_add_u32_e32 v56, 64, v56
	s_and_b64 vcc, exec, s[8:9]
	s_mov_b64 s[8:9], -1
	s_cbranch_vccnz .LBB0_355
	s_andn2_b64 vcc, exec, s[22:23]
	s_cbranch_vccnz .LBB0_354
	s_barrier
	s_branch .LBB0_354

; __device__ __forceinline__ unsigned cvt_pk_bf16(float lo, float hi) { unsigned r; asm volatile("v_cvt_pk_bf16_f32 %0, %1, %2" : "=v"(r) : "v"(lo), "v"(hi)); return r; }
; __device__ __forceinline__ unsigned cvt_pk_bf16(float lo, float hi) { const f32x2 v = {lo, hi}; const bf16x2_t b = __builtin_convertvector(v, bf16x2_t); return __builtin_bit_cast(unsigned, b); }
;     __device__ __forceinline__ void operator()(const f32x4 (&acc)[2][2][4][2], const Unit& u, int wr, int wc, int fr, int fq) const {
;         const int row0 = u.pm * BM + wr * 64 + fr, col0 = u.pn * BM + wc * 32 + 8 * fq;
;         u32x4 rb[2][4][2];
; #pragma unroll
;         for (int ai = 0; ai < 2; ++ai)
; #pragma unroll
;             for (int m = 0; m < 4; ++m) { const bf16_t* xq = XB + (size_t)(row0 + ai * HALF + m * 16) * 1024 + col0; rb[ai][m][0] = *(const u32x4*)xq; rb[ai][m][1] = *(const u32x4*)(xq + HALF); }
; #pragma unroll
;         for (int ai = 0; ai < 2; ++ai) {
; #pragma unroll
;             for (int m = 0; m < 4; ++m) {
;                 const int r = row0 + ai * HALF + m * 16;
;                 bf16_t* xp = XB + (size_t)r * 1024 + col0;
;                 const u32x4 b0 = rb[ai][m][0], b1 = rb[ai][m][1];
;                 float ss = 0.f;
; #pragma unroll
;                 for (int bj = 0; bj < 2; ++bj) {
;                     const u32x4 b = bj ? b1 : b0;
;                     f32x4 v0, v1;
;                     v0[0] = __uint_as_float(b.x << 16); v0[1] = __uint_as_float(b.x & 0xffff0000u); v0[2] = __uint_as_float(b.y << 16); v0[3] = __uint_as_float(b.y & 0xffff0000u);
;                     v1[0] = __uint_as_float(b.z << 16); v1[1] = __uint_as_float(b.z & 0xffff0000u); v1[2] = __uint_as_float(b.w << 16); v1[3] = __uint_as_float(b.w & 0xffff0000u);
;                     v0 += acc[ai][bj][m][0] * alpha; v1 += acc[ai][bj][m][1] * alpha;
;                     ss += (v0[0] * v0[0] + v0[1] * v0[1]) + (v0[2] * v0[2] + v0[3] * v0[3]) + (v1[0] * v1[0] + v1[1] * v1[1]) + (v1[2] * v1[2] + v1[3] * v1[3]);
;                     u32x4 w; w.x = cvt_pk_bf16(v0[0], v0[1]); w.y = cvt_pk_bf16(v0[2], v0[3]); w.z = cvt_pk_bf16(v1[0], v1[1]); w.w = cvt_pk_bf16(v1[2], v1[3]);
;                     *(u32x4*)(xp + bj * HALF) = w;
.LBB0_924:
	v_lshl_or_b32 v128, s18, 8, v245
	v_lshl_add_u32 v130, s4, 8, v193
	v_lshlrev_b32_e32 v128, 1, v128
	v_mov_b32_e32 v129, 0
	v_mov_b32_e32 v131, 0
	s_mov_b32 s84, 0x8000
	s_mov_b32 s85, 0
	s_mov_b32 s86, 0x40000
	s_mov_b32 s87, 0
	v_lshl_add_u64 v[132:133], s[34:35], 0, v[128:129]
	v_lshlrev_b32_e32 v228, 11, v130
	v_mov_b32_e32 v229, 0
	v_lshl_add_u64 v[132:133], v[132:133], 0, v[228:229]
	v_lshl_add_u64 v[140:141], v[132:133], 0, s[86:87]
	v_lshl_add_u64 v[134:135], v[132:133], 0, s[84:85]
	v_lshl_add_u64 v[136:137], v[134:135], 0, s[84:85]
	v_lshl_add_u64 v[138:139], v[136:137], 0, s[84:85]
	v_lshl_add_u64 v[142:143], v[140:141], 0, s[84:85]
	v_lshl_add_u64 v[144:145], v[142:143], 0, s[84:85]
	v_lshl_add_u64 v[146:147], v[144:145], 0, s[84:85]
	global_load_dwordx4 v[148:151], v[132:133], off
	global_load_dwordx4 v[152:155], v[132:133], off offset:256
	global_load_dwordx4 v[156:159], v[134:135], off
	global_load_dwordx4 v[160:163], v[134:135], off offset:256
	global_load_dwordx4 v[164:167], v[136:137], off
	global_load_dwordx4 v[168:171], v[136:137], off offset:256
	global_load_dwordx4 v[172:175], v[138:139], off
	global_load_dwordx4 v[176:179], v[138:139], off offset:256
	global_load_dwordx4 v[180:183], v[140:141], off
	global_load_dwordx4 v[184:187], v[140:141], off offset:256
	global_load_dwordx4 v[188:191], v[142:143], off
	global_load_dwordx4 v[208:211], v[142:143], off offset:256
	global_load_dwordx4 v[212:215], v[144:145], off
	global_load_dwordx4 v[216:219], v[144:145], off offset:256
	global_load_dwordx4 v[220:223], v[146:147], off
	global_load_dwordx4 v[224:227], v[146:147], off offset:256
	v_xor_b32_e32 v238, 16, v246
	v_xor_b32_e32 v239, 32, v246
	v_lshlrev_b32_e32 v238, 2, v238
	v_lshlrev_b32_e32 v239, 2, v239
	s_lshl_b32 s90, s18, 2
	s_add_i32 s90, s90, s64
	s_lshl_b32 s90, s90, 2
	s_mov_b32 s91, 0
	v_lshlrev_b32_e32 v230, 6, v130
	v_mov_b32_e32 v231, 0
	v_lshl_add_u64 v[240:241], s[44:45], 0, v[230:231]
	v_lshl_add_u64 v[240:241], v[240:241], 0, s[90:91]
	s_waitcnt vmcnt(0)
	v_lshlrev_b32_e32 v228, 16, v148
	v_and_b32_e32 v229, 0xffff0000, v148
	v_lshlrev_b32_e32 v230, 16, v149
	v_and_b32_e32 v231, 0xffff0000, v149
	v_lshlrev_b32_e32 v232, 16, v150
	v_and_b32_e32 v233, 0xffff0000, v150
	v_lshlrev_b32_e32 v234, 16, v151
	v_and_b32_e32 v235, 0xffff0000, v151
	v_pk_add_f32 v[120:121], v[120:121], v[228:229]
	v_pk_add_f32 v[122:123], v[122:123], v[230:231]
	v_pk_add_f32 v[124:125], v[124:125], v[232:233]
	v_pk_add_f32 v[126:127], v[126:127], v[234:235]
	v_pk_mul_f32 v[236:237], v[120:121], v[120:121]
	v_pk_fma_f32 v[236:237], v[122:123], v[122:123], v[236:237]
	v_pk_fma_f32 v[236:237], v[124:125], v[124:125], v[236:237]
	v_pk_fma_f32 v[236:237], v[126:127], v[126:127], v[236:237]
	v_cvt_pk_bf16_f32 v148, v120, v121
	v_cvt_pk_bf16_f32 v149, v122, v123
	v_cvt_pk_bf16_f32 v150, v124, v125
	v_cvt_pk_bf16_f32 v151, v126, v127
	global_store_dwordx4 v[132:133], v[148:151], off
	v_lshlrev_b32_e32 v228, 16, v152
	v_and_b32_e32 v229, 0xffff0000, v152
	v_lshlrev_b32_e32 v230, 16, v153
	v_and_b32_e32 v231, 0xffff0000, v153
	v_lshlrev_b32_e32 v232, 16, v154
	v_and_b32_e32 v233, 0xffff0000, v154
	v_lshlrev_b32_e32 v234, 16, v155
	v_and_b32_e32 v235, 0xffff0000, v155
	v_pk_add_f32 v[116:117], v[116:117], v[228:229]
	v_pk_add_f32 v[118:119], v[118:119], v[230:231]
	v_pk_add_f32 v[112:113], v[112:113], v[232:233]
	v_pk_add_f32 v[114:115], v[114:115], v[234:235]
	v_pk_fma_f32 v[236:237], v[116:117], v[116:117], v[236:237]
	v_pk_fma_f32 v[236:237], v[118:119], v[118:119], v[236:237]
	v_pk_fma_f32 v[236:237], v[112:113], v[112:113], v[236:237]
	v_pk_fma_f32 v[236:237], v[114:115], v[114:115], v[236:237]
	v_cvt_pk_bf16_f32 v152, v116, v117
	v_cvt_pk_bf16_f32 v153, v118, v119
	v_cvt_pk_bf16_f32 v154, v112, v113
	v_cvt_pk_bf16_f32 v155, v114, v115
	global_store_dwordx4 v[132:133], v[152:155], off offset:256
	s_nop 0
	v_add_f32_e32 v132, v236, v237
	v_lshlrev_b32_e32 v228, 16, v156
	v_and_b32_e32 v229, 0xffff0000, v156
	v_lshlrev_b32_e32 v230, 16, v157
	v_and_b32_e32 v231, 0xffff0000, v157
	v_lshlrev_b32_e32 v232, 16, v158
	v_and_b32_e32 v233, 0xffff0000, v158
	v_lshlrev_b32_e32 v234, 16, v159
	v_and_b32_e32 v235, 0xffff0000, v159
	v_pk_add_f32 v[108:109], v[108:109], v[228:229]
	v_pk_add_f32 v[110:111], v[110:111], v[230:231]
	v_pk_add_f32 v[104:105], v[104:105], v[232:233]
	v_pk_add_f32 v[106:107], v[106:107], v[234:235]
	v_pk_mul_f32 v[236:237], v[108:109], v[108:109]
	v_pk_fma_f32 v[236:237], v[110:111], v[110:111], v[236:237]
	v_pk_fma_f32 v[236:237], v[104:105], v[104:105], v[236:237]
	v_pk_fma_f32 v[236:237], v[106:107], v[106:107], v[236:237]
	v_cvt_pk_bf16_f32 v156, v108, v109
	v_cvt_pk_bf16_f32 v157, v110, v111
	v_cvt_pk_bf16_f32 v158, v104, v105
	v_cvt_pk_bf16_f32 v159, v106, v107
	global_store_dwordx4 v[134:135], v[156:159], off
	v_lshlrev_b32_e32 v228, 16, v160
	v_and_b32_e32 v229, 0xffff0000, v160
	v_lshlrev_b32_e32 v230, 16, v161
	v_and_b32_e32 v231, 0xffff0000, v161
	v_lshlrev_b32_e32 v232, 16, v162
	v_and_b32_e32 v233, 0xffff0000, v162
	v_lshlrev_b32_e32 v234, 16, v163
	v_and_b32_e32 v235, 0xffff0000, v163
	v_pk_add_f32 v[100:101], v[100:101], v[228:229]
	v_pk_add_f32 v[102:103], v[102:103], v[230:231]
	v_pk_add_f32 v[96:97], v[96:97], v[232:233]
	v_pk_add_f32 v[98:99], v[98:99], v[234:235]
	v_pk_fma_f32 v[236:237], v[100:101], v[100:101], v[236:237]
	v_pk_fma_f32 v[236:237], v[102:103], v[102:103], v[236:237]
	v_pk_fma_f32 v[236:237], v[96:97], v[96:97], v[236:237]
	v_pk_fma_f32 v[236:237], v[98:99], v[98:99], v[236:237]
	v_cvt_pk_bf16_f32 v160, v100, v101
	v_cvt_pk_bf16_f32 v161, v102, v103
	v_cvt_pk_bf16_f32 v162, v96, v97
; __device__ __forceinline__ unsigned cvt_pk_bf16(float lo, float hi) { unsigned r; asm volatile("v_cvt_pk_bf16_f32 %0, %1, %2" : "=v"(r) : "v"(lo), "v"(hi)); return r; }
; __device__ __forceinline__ unsigned cvt_pk_bf16(float lo, float hi) { const f32x2 v = {lo, hi}; const bf16x2_t b = __builtin_convertvector(v, bf16x2_t); return __builtin_bit_cast(unsigned, b); }
;     __device__ __forceinline__ void operator()(const f32x4 (&acc)[2][2][4][2], const Unit& u, int wr, int wc, int fr, int fq) const {
;     ...
;                 const u32x4 b0 = rb[ai][m][0], b1 = rb[ai][m][1];
;                 float ss = 0.f;
; #pragma unroll
;                 for (int bj = 0; bj < 2; ++bj) {
;                     const u32x4 b = bj ? b1 : b0;
;                     f32x4 v0, v1;
;                     v0[0] = __uint_as_float(b.x << 16); v0[1] = __uint_as_float(b.x & 0xffff0000u); v0[2] = __uint_as_float(b.y << 16); v0[3] = __uint_as_float(b.y & 0xffff0000u);
;                     v1[0] = __uint_as_float(b.z << 16); v1[1] = __uint_as_float(b.z & 0xffff0000u); v1[2] = __uint_as_float(b.w << 16); v1[3] = __uint_as_float(b.w & 0xffff0000u);
;                     v0 += acc[ai][bj][m][0] * alpha; v1 += acc[ai][bj][m][1] * alpha;
;                     ss += (v0[0] * v0[0] + v0[1] * v0[1]) + (v0[2] * v0[2] + v0[3] * v0[3]) + (v1[0] * v1[0] + v1[1] * v1[1]) + (v1[2] * v1[2] + v1[3] * v1[3]);
;                     u32x4 w; w.x = cvt_pk_bf16(v0[0], v0[1]); w.y = cvt_pk_bf16(v0[2], v0[3]); w.z = cvt_pk_bf16(v1[0], v1[1]); w.w = cvt_pk_bf16(v1[2], v1[3]);
;                     *(u32x4*)(xp + bj * HALF) = w;
	v_cvt_pk_bf16_f32 v163, v98, v99
	global_store_dwordx4 v[134:135], v[160:163], off offset:256
	s_nop 0
	v_add_f32_e32 v134, v236, v237
	v_lshlrev_b32_e32 v228, 16, v164
	v_and_b32_e32 v229, 0xffff0000, v164
	v_lshlrev_b32_e32 v230, 16, v165
	v_and_b32_e32 v231, 0xffff0000, v165
	v_lshlrev_b32_e32 v232, 16, v166
	v_and_b32_e32 v233, 0xffff0000, v166
	v_lshlrev_b32_e32 v234, 16, v167
	v_and_b32_e32 v235, 0xffff0000, v167
	v_pk_add_f32 v[92:93], v[92:93], v[228:229]
	v_pk_add_f32 v[94:95], v[94:95], v[230:231]
	v_pk_add_f32 v[88:89], v[88:89], v[232:233]
	v_pk_add_f32 v[90:91], v[90:91], v[234:235]
	v_pk_mul_f32 v[236:237], v[92:93], v[92:93]
	v_pk_fma_f32 v[236:237], v[94:95], v[94:95], v[236:237]
	v_pk_fma_f32 v[236:237], v[88:89], v[88:89], v[236:237]
	v_pk_fma_f32 v[236:237], v[90:91], v[90:91], v[236:237]
	v_cvt_pk_bf16_f32 v164, v92, v93
	v_cvt_pk_bf16_f32 v165, v94, v95
	v_cvt_pk_bf16_f32 v166, v88, v89
	v_cvt_pk_bf16_f32 v167, v90, v91
	global_store_dwordx4 v[136:137], v[164:167], off
	v_lshlrev_b32_e32 v228, 16, v168
	v_and_b32_e32 v229, 0xffff0000, v168
	v_lshlrev_b32_e32 v230, 16, v169
	v_and_b32_e32 v231, 0xffff0000, v169
	v_lshlrev_b32_e32 v232, 16, v170
	v_and_b32_e32 v233, 0xffff0000, v170
	v_lshlrev_b32_e32 v234, 16, v171
	v_and_b32_e32 v235, 0xffff0000, v171
	v_pk_add_f32 v[84:85], v[84:85], v[228:229]
	v_pk_add_f32 v[86:87], v[86:87], v[230:231]
	v_pk_add_f32 v[80:81], v[80:81], v[232:233]
	v_pk_add_f32 v[82:83], v[82:83], v[234:235]
	v_pk_fma_f32 v[236:237], v[84:85], v[84:85], v[236:237]
	v_pk_fma_f32 v[236:237], v[86:87], v[86:87], v[236:237]
	v_pk_fma_f32 v[236:237], v[80:81], v[80:81], v[236:237]
	v_pk_fma_f32 v[236:237], v[82:83], v[82:83], v[236:237]
	v_cvt_pk_bf16_f32 v168, v84, v85
	v_cvt_pk_bf16_f32 v169, v86, v87
	v_cvt_pk_bf16_f32 v170, v80, v81
	v_cvt_pk_bf16_f32 v171, v82, v83
	global_store_dwordx4 v[136:137], v[168:171], off offset:256
	s_nop 0
	v_add_f32_e32 v136, v236, v237
	v_lshlrev_b32_e32 v228, 16, v172
	v_and_b32_e32 v229, 0xffff0000, v172
	v_lshlrev_b32_e32 v230, 16, v173
	v_and_b32_e32 v231, 0xffff0000, v173
	v_lshlrev_b32_e32 v232, 16, v174
	v_and_b32_e32 v233, 0xffff0000, v174
	v_lshlrev_b32_e32 v234, 16, v175
	v_and_b32_e32 v235, 0xffff0000, v175
	v_pk_add_f32 v[76:77], v[76:77], v[228:229]
	v_pk_add_f32 v[78:79], v[78:79], v[230:231]
	v_pk_add_f32 v[72:73], v[72:73], v[232:233]
	v_pk_add_f32 v[74:75], v[74:75], v[234:235]
	v_pk_mul_f32 v[236:237], v[76:77], v[76:77]
	v_pk_fma_f32 v[236:237], v[78:79], v[78:79], v[236:237]
	v_pk_fma_f32 v[236:237], v[72:73], v[72:73], v[236:237]
	v_pk_fma_f32 v[236:237], v[74:75], v[74:75], v[236:237]
	v_cvt_pk_bf16_f32 v172, v76, v77
	v_cvt_pk_bf16_f32 v173, v78, v79
	v_cvt_pk_bf16_f32 v174, v72, v73
	v_cvt_pk_bf16_f32 v175, v74, v75
	global_store_dwordx4 v[138:139], v[172:175], off
	v_lshlrev_b32_e32 v228, 16, v176
	v_and_b32_e32 v229, 0xffff0000, v176
	v_lshlrev_b32_e32 v230, 16, v177
	v_and_b32_e32 v231, 0xffff0000, v177
	v_lshlrev_b32_e32 v232, 16, v178
	v_and_b32_e32 v233, 0xffff0000, v178
	v_lshlrev_b32_e32 v234, 16, v179
	v_and_b32_e32 v235, 0xffff0000, v179
	v_pk_add_f32 v[68:69], v[68:69], v[228:229]
	v_pk_add_f32 v[70:71], v[70:71], v[230:231]
	v_pk_add_f32 v[64:65], v[64:65], v[232:233]
	v_pk_add_f32 v[66:67], v[66:67], v[234:235]
	v_pk_fma_f32 v[236:237], v[68:69], v[68:69], v[236:237]
	v_pk_fma_f32 v[236:237], v[70:71], v[70:71], v[236:237]
	v_pk_fma_f32 v[236:237], v[64:65], v[64:65], v[236:237]
	v_pk_fma_f32 v[236:237], v[66:67], v[66:67], v[236:237]
	v_cvt_pk_bf16_f32 v176, v68, v69
	v_cvt_pk_bf16_f32 v177, v70, v71
	v_cvt_pk_bf16_f32 v178, v64, v65
	v_cvt_pk_bf16_f32 v179, v66, v67
	global_store_dwordx4 v[138:139], v[176:179], off offset:256
	s_nop 0
	v_add_f32_e32 v138, v236, v237
	v_lshlrev_b32_e32 v228, 16, v180
	v_and_b32_e32 v229, 0xffff0000, v180
	v_lshlrev_b32_e32 v230, 16, v181
	v_and_b32_e32 v231, 0xffff0000, v181
	v_lshlrev_b32_e32 v232, 16, v182
	v_and_b32_e32 v233, 0xffff0000, v182
	v_lshlrev_b32_e32 v234, 16, v183
	v_and_b32_e32 v235, 0xffff0000, v183
	v_pk_add_f32 v[60:61], v[60:61], v[228:229]
	v_pk_add_f32 v[62:63], v[62:63], v[230:231]
	v_pk_add_f32 v[56:57], v[56:57], v[232:233]
	v_pk_add_f32 v[58:59], v[58:59], v[234:235]
	v_pk_mul_f32 v[236:237], v[60:61], v[60:61]
	v_pk_fma_f32 v[236:237], v[62:63], v[62:63], v[236:237]
	v_pk_fma_f32 v[236:237], v[56:57], v[56:57], v[236:237]
	v_pk_fma_f32 v[236:237], v[58:59], v[58:59], v[236:237]
	v_cvt_pk_bf16_f32 v180, v60, v61
	v_cvt_pk_bf16_f32 v181, v62, v63
	v_cvt_pk_bf16_f32 v182, v56, v57
	v_cvt_pk_bf16_f32 v183, v58, v59
	global_store_dwordx4 v[140:141], v[180:183], off
	v_lshlrev_b32_e32 v228, 16, v184
	v_and_b32_e32 v229, 0xffff0000, v184
	v_lshlrev_b32_e32 v230, 16, v185
	v_and_b32_e32 v231, 0xffff0000, v185
	v_lshlrev_b32_e32 v232, 16, v186
	v_and_b32_e32 v233, 0xffff0000, v186
	v_lshlrev_b32_e32 v234, 16, v187
	v_and_b32_e32 v235, 0xffff0000, v187
	v_pk_add_f32 v[52:53], v[52:53], v[228:229]
	v_pk_add_f32 v[54:55], v[54:55], v[230:231]
	v_pk_add_f32 v[48:49], v[48:49], v[232:233]
	v_pk_add_f32 v[50:51], v[50:51], v[234:235]
	v_pk_fma_f32 v[236:237], v[52:53], v[52:53], v[236:237]
	v_pk_fma_f32 v[236:237], v[54:55], v[54:55], v[236:237]
	v_pk_fma_f32 v[236:237], v[48:49], v[48:49], v[236:237]
	v_pk_fma_f32 v[236:237], v[50:51], v[50:51], v[236:237]
	v_cvt_pk_bf16_f32 v184, v52, v53
	v_cvt_pk_bf16_f32 v185, v54, v55
	v_cvt_pk_bf16_f32 v186, v48, v49
	v_cvt_pk_bf16_f32 v187, v50, v51
	global_store_dwordx4 v[140:141], v[184:187], off offset:256
	s_nop 0
	v_add_f32_e32 v140, v236, v237
	v_lshlrev_b32_e32 v228, 16, v188
	v_and_b32_e32 v229, 0xffff0000, v188
	v_lshlrev_b32_e32 v230, 16, v189
; __device__ __forceinline__ unsigned cvt_pk_bf16(float lo, float hi) { unsigned r; asm volatile("v_cvt_pk_bf16_f32 %0, %1, %2" : "=v"(r) : "v"(lo), "v"(hi)); return r; }
; __device__ __forceinline__ unsigned cvt_pk_bf16(float lo, float hi) { const f32x2 v = {lo, hi}; const bf16x2_t b = __builtin_convertvector(v, bf16x2_t); return __builtin_bit_cast(unsigned, b); }
;     __device__ __forceinline__ void operator()(const f32x4 (&acc)[2][2][4][2], const Unit& u, int wr, int wc, int fr, int fq) const {
;     ...
;                 const u32x4 b0 = rb[ai][m][0], b1 = rb[ai][m][1];
;                 float ss = 0.f;
; #pragma unroll
;                 for (int bj = 0; bj < 2; ++bj) {
;                     const u32x4 b = bj ? b1 : b0;
;                     f32x4 v0, v1;
;                     v0[0] = __uint_as_float(b.x << 16); v0[1] = __uint_as_float(b.x & 0xffff0000u); v0[2] = __uint_as_float(b.y << 16); v0[3] = __uint_as_float(b.y & 0xffff0000u);
;                     v1[0] = __uint_as_float(b.z << 16); v1[1] = __uint_as_float(b.z & 0xffff0000u); v1[2] = __uint_as_float(b.w << 16); v1[3] = __uint_as_float(b.w & 0xffff0000u);
;                     v0 += acc[ai][bj][m][0] * alpha; v1 += acc[ai][bj][m][1] * alpha;
;                     ss += (v0[0] * v0[0] + v0[1] * v0[1]) + (v0[2] * v0[2] + v0[3] * v0[3]) + (v1[0] * v1[0] + v1[1] * v1[1]) + (v1[2] * v1[2] + v1[3] * v1[3]);
;                     u32x4 w; w.x = cvt_pk_bf16(v0[0], v0[1]); w.y = cvt_pk_bf16(v0[2], v0[3]); w.z = cvt_pk_bf16(v1[0], v1[1]); w.w = cvt_pk_bf16(v1[2], v1[3]);
;                     *(u32x4*)(xp + bj * HALF) = w;
;                 }
;                 ss += __shfl_xor(ss, 16); ss += __shfl_xor(ss, 32);
	v_and_b32_e32 v231, 0xffff0000, v189
	v_lshlrev_b32_e32 v232, 16, v190
	v_and_b32_e32 v233, 0xffff0000, v190
	v_lshlrev_b32_e32 v234, 16, v191
	v_and_b32_e32 v235, 0xffff0000, v191
	v_pk_add_f32 v[44:45], v[44:45], v[228:229]
	v_pk_add_f32 v[46:47], v[46:47], v[230:231]
	v_pk_add_f32 v[40:41], v[40:41], v[232:233]
	v_pk_add_f32 v[42:43], v[42:43], v[234:235]
	v_pk_mul_f32 v[236:237], v[44:45], v[44:45]
	v_pk_fma_f32 v[236:237], v[46:47], v[46:47], v[236:237]
	v_pk_fma_f32 v[236:237], v[40:41], v[40:41], v[236:237]
	v_pk_fma_f32 v[236:237], v[42:43], v[42:43], v[236:237]
	v_cvt_pk_bf16_f32 v188, v44, v45
	v_cvt_pk_bf16_f32 v189, v46, v47
	v_cvt_pk_bf16_f32 v190, v40, v41
	v_cvt_pk_bf16_f32 v191, v42, v43
	global_store_dwordx4 v[142:143], v[188:191], off
	v_lshlrev_b32_e32 v228, 16, v208
	v_and_b32_e32 v229, 0xffff0000, v208
	v_lshlrev_b32_e32 v230, 16, v209
	v_and_b32_e32 v231, 0xffff0000, v209
	v_lshlrev_b32_e32 v232, 16, v210
	v_and_b32_e32 v233, 0xffff0000, v210
	v_lshlrev_b32_e32 v234, 16, v211
	v_and_b32_e32 v235, 0xffff0000, v211
	v_pk_add_f32 v[36:37], v[36:37], v[228:229]
	v_pk_add_f32 v[38:39], v[38:39], v[230:231]
	v_pk_add_f32 v[32:33], v[32:33], v[232:233]
	v_pk_add_f32 v[34:35], v[34:35], v[234:235]
	v_pk_fma_f32 v[236:237], v[36:37], v[36:37], v[236:237]
	v_pk_fma_f32 v[236:237], v[38:39], v[38:39], v[236:237]
	v_pk_fma_f32 v[236:237], v[32:33], v[32:33], v[236:237]
	v_pk_fma_f32 v[236:237], v[34:35], v[34:35], v[236:237]
	v_cvt_pk_bf16_f32 v208, v36, v37
	v_cvt_pk_bf16_f32 v209, v38, v39
	v_cvt_pk_bf16_f32 v210, v32, v33
	v_cvt_pk_bf16_f32 v211, v34, v35
	global_store_dwordx4 v[142:143], v[208:211], off offset:256
	s_nop 0
	v_add_f32_e32 v142, v236, v237
	v_lshlrev_b32_e32 v228, 16, v212
	v_and_b32_e32 v229, 0xffff0000, v212
	v_lshlrev_b32_e32 v230, 16, v213
	v_and_b32_e32 v231, 0xffff0000, v213
	v_lshlrev_b32_e32 v232, 16, v214
	v_and_b32_e32 v233, 0xffff0000, v214
	v_lshlrev_b32_e32 v234, 16, v215
	v_and_b32_e32 v235, 0xffff0000, v215
	v_pk_add_f32 v[28:29], v[28:29], v[228:229]
	v_pk_add_f32 v[30:31], v[30:31], v[230:231]
	v_pk_add_f32 v[24:25], v[24:25], v[232:233]
	v_pk_add_f32 v[26:27], v[26:27], v[234:235]
	v_pk_mul_f32 v[236:237], v[28:29], v[28:29]
	v_pk_fma_f32 v[236:237], v[30:31], v[30:31], v[236:237]
	v_pk_fma_f32 v[236:237], v[24:25], v[24:25], v[236:237]
	v_pk_fma_f32 v[236:237], v[26:27], v[26:27], v[236:237]
	v_cvt_pk_bf16_f32 v212, v28, v29
	v_cvt_pk_bf16_f32 v213, v30, v31
	v_cvt_pk_bf16_f32 v214, v24, v25
	v_cvt_pk_bf16_f32 v215, v26, v27
	global_store_dwordx4 v[144:145], v[212:215], off
	v_lshlrev_b32_e32 v228, 16, v216
	v_and_b32_e32 v229, 0xffff0000, v216
	v_lshlrev_b32_e32 v230, 16, v217
	v_and_b32_e32 v231, 0xffff0000, v217
	v_lshlrev_b32_e32 v232, 16, v218
	v_and_b32_e32 v233, 0xffff0000, v218
	v_lshlrev_b32_e32 v234, 16, v219
	v_and_b32_e32 v235, 0xffff0000, v219
	v_pk_add_f32 v[20:21], v[20:21], v[228:229]
	v_pk_add_f32 v[22:23], v[22:23], v[230:231]
	v_pk_add_f32 v[16:17], v[16:17], v[232:233]
	v_pk_add_f32 v[18:19], v[18:19], v[234:235]
	v_pk_fma_f32 v[236:237], v[20:21], v[20:21], v[236:237]
	v_pk_fma_f32 v[236:237], v[22:23], v[22:23], v[236:237]
	v_pk_fma_f32 v[236:237], v[16:17], v[16:17], v[236:237]
	v_pk_fma_f32 v[236:237], v[18:19], v[18:19], v[236:237]
	v_cvt_pk_bf16_f32 v216, v20, v21
	v_cvt_pk_bf16_f32 v217, v22, v23
	v_cvt_pk_bf16_f32 v218, v16, v17
	v_cvt_pk_bf16_f32 v219, v18, v19
	global_store_dwordx4 v[144:145], v[216:219], off offset:256
	s_nop 0
	v_add_f32_e32 v144, v236, v237
	v_lshlrev_b32_e32 v228, 16, v220
	v_and_b32_e32 v229, 0xffff0000, v220
	v_lshlrev_b32_e32 v230, 16, v221
	v_and_b32_e32 v231, 0xffff0000, v221
	v_lshlrev_b32_e32 v232, 16, v222
	v_and_b32_e32 v233, 0xffff0000, v222
	v_lshlrev_b32_e32 v234, 16, v223
	v_and_b32_e32 v235, 0xffff0000, v223
	v_pk_add_f32 v[12:13], v[12:13], v[228:229]
	v_pk_add_f32 v[14:15], v[14:15], v[230:231]
	v_pk_add_f32 v[8:9], v[8:9], v[232:233]
	v_pk_add_f32 v[10:11], v[10:11], v[234:235]
	v_pk_mul_f32 v[236:237], v[12:13], v[12:13]
	v_pk_fma_f32 v[236:237], v[14:15], v[14:15], v[236:237]
	v_pk_fma_f32 v[236:237], v[8:9], v[8:9], v[236:237]
	v_pk_fma_f32 v[236:237], v[10:11], v[10:11], v[236:237]
	v_cvt_pk_bf16_f32 v220, v12, v13
	v_cvt_pk_bf16_f32 v221, v14, v15
	v_cvt_pk_bf16_f32 v222, v8, v9
	v_cvt_pk_bf16_f32 v223, v10, v11
	global_store_dwordx4 v[146:147], v[220:223], off
	v_lshlrev_b32_e32 v228, 16, v224
	v_and_b32_e32 v229, 0xffff0000, v224
	v_lshlrev_b32_e32 v230, 16, v225
	v_and_b32_e32 v231, 0xffff0000, v225
	v_lshlrev_b32_e32 v232, 16, v226
	v_and_b32_e32 v233, 0xffff0000, v226
	v_lshlrev_b32_e32 v234, 16, v227
	v_and_b32_e32 v235, 0xffff0000, v227
	v_pk_add_f32 v[4:5], v[4:5], v[228:229]
	v_pk_add_f32 v[6:7], v[6:7], v[230:231]
	v_pk_add_f32 v[0:1], v[0:1], v[232:233]
	v_pk_add_f32 v[2:3], v[2:3], v[234:235]
	v_pk_fma_f32 v[236:237], v[4:5], v[4:5], v[236:237]
	v_pk_fma_f32 v[236:237], v[6:7], v[6:7], v[236:237]
	v_pk_fma_f32 v[236:237], v[0:1], v[0:1], v[236:237]
	v_pk_fma_f32 v[236:237], v[2:3], v[2:3], v[236:237]
	v_cvt_pk_bf16_f32 v224, v4, v5
	v_cvt_pk_bf16_f32 v225, v6, v7
	v_cvt_pk_bf16_f32 v226, v0, v1
	v_cvt_pk_bf16_f32 v227, v2, v3
	global_store_dwordx4 v[146:147], v[224:227], off offset:256
	s_nop 0
	v_add_f32_e32 v146, v236, v237
	ds_bpermute_b32 v133, v238, v132
	ds_bpermute_b32 v135, v238, v134
	ds_bpermute_b32 v137, v238, v136
	ds_bpermute_b32 v139, v238, v138
	ds_bpermute_b32 v141, v238, v140
	ds_bpermute_b32 v143, v238, v142
	ds_bpermute_b32 v145, v238, v144
	ds_bpermute_b32 v147, v238, v146
	s_waitcnt lgkmcnt(7)
;     __device__ __forceinline__ void operator()(const f32x4 (&acc)[2][2][4][2], const Unit& u, int wr, int wc, int fr, int fq) const {
;     ...
;                 ss += __shfl_xor(ss, 16); ss += __shfl_xor(ss, 32);
;                 if (fq == 0) SS[(size_t)r * 16 + u.pn * 4 + wc] = ss;
	v_add_f32_e32 v132, v132, v133
	s_waitcnt lgkmcnt(6)
	v_add_f32_e32 v134, v134, v135
	s_waitcnt lgkmcnt(5)
	v_add_f32_e32 v136, v136, v137
	s_waitcnt lgkmcnt(4)
	v_add_f32_e32 v138, v138, v139
	s_waitcnt lgkmcnt(3)
	v_add_f32_e32 v140, v140, v141
	s_waitcnt lgkmcnt(2)
	v_add_f32_e32 v142, v142, v143
	s_waitcnt lgkmcnt(1)
	v_add_f32_e32 v144, v144, v145
	s_waitcnt lgkmcnt(0)
	v_add_f32_e32 v146, v146, v147
	ds_bpermute_b32 v133, v239, v132
	ds_bpermute_b32 v135, v239, v134
	ds_bpermute_b32 v137, v239, v136
	ds_bpermute_b32 v139, v239, v138
	ds_bpermute_b32 v141, v239, v140
	ds_bpermute_b32 v143, v239, v142
	ds_bpermute_b32 v145, v239, v144
	ds_bpermute_b32 v147, v239, v146
	s_waitcnt lgkmcnt(7)
	v_add_f32_e32 v132, v132, v133
	s_waitcnt lgkmcnt(6)
	v_add_f32_e32 v134, v134, v135
	s_waitcnt lgkmcnt(5)
	v_add_f32_e32 v136, v136, v137
	s_waitcnt lgkmcnt(4)
	v_add_f32_e32 v138, v138, v139
	s_waitcnt lgkmcnt(3)
	v_add_f32_e32 v140, v140, v141
	s_waitcnt lgkmcnt(2)
	v_add_f32_e32 v142, v142, v143
	s_waitcnt lgkmcnt(1)
	v_add_f32_e32 v144, v144, v145
	s_waitcnt lgkmcnt(0)
	v_add_f32_e32 v146, v146, v147
	s_and_saveexec_b64 s[88:89], s[0:1]
	global_store_dword v[240:241], v132, off
	global_store_dword v[240:241], v134, off offset:1024
	global_store_dword v[240:241], v136, off offset:2048
	global_store_dword v[240:241], v138, off offset:3072
	s_movk_i32 s84, 0x2000
	v_lshl_add_u64 v[240:241], v[240:241], 0, s[84:85]
	global_store_dword v[240:241], v140, off
	global_store_dword v[240:241], v142, off offset:1024
	global_store_dword v[240:241], v144, off offset:2048
	global_store_dword v[240:241], v146, off offset:3072
	s_or_b64 exec, exec, s[88:89]
	v_and_b32_e32 v112, 64, v246
	v_add_u32_e32 v112, 64, v112
	s_and_b64 vcc, exec, s[6:7]
	s_mov_b64 s[6:7], -1
	s_cbranch_vccnz .LBB0_908
	s_andn2_b64 vcc, exec, s[20:21]
	s_cbranch_vccnz .LBB0_907
	s_barrier
	s_branch .LBB0_907

;     __host__ __device__ bool next(int i, Unit& u) const { const int idx = first + i; if (idx >= last) return false; u.pm = idx >> 2; u.pn = idx & 3; return true; }
; #define PG8_STAGE(bufoff, gbase, voff) do { _Pragma("unroll") for (int _i = 0; _i < 2; ++_i) \
;         __builtin_amdgcn_global_load_lds((const unsigned*)((const char*)(gbase) + (voff)[_i]), (PG8_LAS unsigned*)(lds + (bufoff) + ldsw + _i * 8192), 16, 0, 0); } while (0)
; #define PG8_LDA(dst, b, h) do { _Pragma("unroll") for (int m = 0; m < 4; ++m) _Pragma("unroll") for (int k = 0; k < 2; ++k) dst[m][k] = *(const PG8_LAS bf16x8*)(lds + PG8_SA(b, h) + aoff + m * 2048 + k * 1024); } while (0)
; #define PG8_LDB(dst, b, h) do { _Pragma("unroll") for (int n = 0; n < 2; ++n) _Pragma("unroll") for (int k = 0; k < 2; ++k) dst[n][k] = *(const PG8_LAS bf16x8*)(lds + PG8_SB(b, h) + boff + n * 2048 + k * 1024); } while (0)
; template <class Epi, class Sched, bool ALIGN_EPI = false, bool SP2 = false>
; __device__ __forceinline__ void gemm_phase(PG8_LAS unsigned char* lds, const Gemm g, const Sched& S, const Epi& E) {
;     ...
;     for (;;) {
;         const bool has_next = S.next(ui + 1, nxt);
;         const char* nA = has_next ? (const char*)g.A + (size_t)nxt.pm * tstep : cA; const char* nB = has_next ? (const char*)g.Bt + (size_t)nxt.pn * tstep : cB;
;         asm volatile(".p2align 8");
;         for (int t = 0; t < nt; t += 2) {
;             const bool last = (t == nt - 2);
;             const char* a1 = cA + (size_t)(t + 1) * kstep;
;             const char* a2 = last ? nA : cA + (size_t)(t + 2) * kstep; const char* b2 = last ? nB : cB + (size_t)(t + 2) * kstep;
;             const char* a3 = a2 + kstep; const char* b3 = b2 + kstep;
;             if (last && has_next) S.a_ready(nxt);
;             if constexpr (SP2) {
;             PG8_LDB(B0, 0, 0); PG8_LDB(B1, 0, 1); PG8_SCHED; PG8_LDA(At, 0, 0); PG8_STAGE(PG8_SA(1, 1), a1 + hstep, voffA);
;             PG8_WAIT_V(8); PG8_WAIT_L(0); PG8_BAR; PG8_MMA(0, 0, At, B0); PG8_MMA(0, 1, At, B1); PG8_BAR; PG8_SCHED;
;     ...
; #pragma unroll
;         for (int a = 0; a < 2; ++a)
; #pragma unroll
;             for (int b = 0; b < 2; ++b)
; #pragma unroll
;                 for (int m = 0; m < 4; ++m)
; #pragma unroll
;                     for (int n = 0; n < 2; ++n) acc[a][b][m][n] = (f32x4){0.f, 0.f, 0.f, 0.f};
;         cur = nxt; cA = nA; cB = nB; ++ui;
.LBB0_1116:
	v_mov_b64_e32 v[0:1], 0
	v_mov_b64_e32 v[2:3], 0
	v_mov_b64_e32 v[4:5], 0
	v_mov_b64_e32 v[6:7], 0
	v_mov_b64_e32 v[8:9], 0
	v_mov_b64_e32 v[10:11], 0
	v_mov_b64_e32 v[12:13], 0
	v_mov_b64_e32 v[14:15], 0
	v_mov_b64_e32 v[16:17], 0
	v_mov_b64_e32 v[18:19], 0
	v_mov_b64_e32 v[20:21], 0
	v_mov_b64_e32 v[22:23], 0
	v_mov_b64_e32 v[24:25], 0
	v_mov_b64_e32 v[26:27], 0
	v_mov_b64_e32 v[28:29], 0
	v_mov_b64_e32 v[30:31], 0
	v_mov_b64_e32 v[32:33], 0
	v_mov_b64_e32 v[34:35], 0
	v_mov_b64_e32 v[36:37], 0
	v_mov_b64_e32 v[38:39], 0
	v_mov_b64_e32 v[40:41], 0
	v_mov_b64_e32 v[42:43], 0
	v_mov_b64_e32 v[44:45], 0
	v_mov_b64_e32 v[46:47], 0
	v_mov_b64_e32 v[48:49], 0
	v_mov_b64_e32 v[50:51], 0
	v_mov_b64_e32 v[52:53], 0
	v_mov_b64_e32 v[54:55], 0
	v_mov_b64_e32 v[56:57], 0
	v_mov_b64_e32 v[58:59], 0
	v_mov_b64_e32 v[60:61], 0
	v_mov_b64_e32 v[62:63], 0
	v_mov_b64_e32 v[64:65], 0
	v_mov_b64_e32 v[66:67], 0
	v_mov_b64_e32 v[68:69], 0
	v_mov_b64_e32 v[70:71], 0
	v_mov_b64_e32 v[72:73], 0
	v_mov_b64_e32 v[74:75], 0
	v_mov_b64_e32 v[76:77], 0
	v_mov_b64_e32 v[78:79], 0
	v_mov_b64_e32 v[80:81], 0
	v_mov_b64_e32 v[82:83], 0
	v_mov_b64_e32 v[84:85], 0
	v_mov_b64_e32 v[86:87], 0
	v_mov_b64_e32 v[88:89], 0
	v_mov_b64_e32 v[90:91], 0
	v_mov_b64_e32 v[92:93], 0
	v_mov_b64_e32 v[94:95], 0
	v_mov_b64_e32 v[96:97], 0
	v_mov_b64_e32 v[98:99], 0
	v_mov_b64_e32 v[100:101], 0
	v_mov_b64_e32 v[102:103], 0
	v_mov_b64_e32 v[104:105], 0
	v_mov_b64_e32 v[106:107], 0
	v_mov_b64_e32 v[108:109], 0
	v_mov_b64_e32 v[110:111], 0
	v_mov_b64_e32 v[112:113], 0
	v_mov_b64_e32 v[114:115], 0
	v_mov_b64_e32 v[116:117], 0
	v_mov_b64_e32 v[118:119], 0
	v_mov_b64_e32 v[120:121], 0
	v_mov_b64_e32 v[122:123], 0
	v_mov_b64_e32 v[124:125], 0
	v_mov_b64_e32 v[126:127], 0
	s_andn2_b64 vcc, exec, s[36:37]
	.p2align 8
	s_cbranch_vccnz .LBB0_1120
	s_add_u32 s42, s42, 0x80
	s_addc_u32 s43, s43, 0
	s_add_u32 s4, s54, 0x100
	s_addc_u32 s5, s55, 0
	s_mov_b32 s33, 0
	s_waitcnt vmcnt(0)
.LBB0_1118:
	ds_read_b128 v[142:145], v247
	ds_read_b128 v[146:149], v247 offset:1024
	ds_read_b128 v[150:153], v247 offset:2048
	ds_read_b128 v[154:157], v247 offset:3072
	ds_read_b128 v[158:161], v248
	ds_read_b128 v[162:165], v248 offset:1024
	ds_read_b128 v[166:169], v248 offset:2048
	ds_read_b128 v[170:173], v248 offset:3072
	s_add_i32 s72, s33, 2
	s_add_u32 s54, s42, 0x80
	s_addc_u32 s55, s43, 0
	s_cmp_eq_u32 s62, s33
	s_cselect_b32 s55, s9, s55
	s_cselect_b32 s54, s8, s54
	s_cselect_b32 s75, s41, s5
	s_cselect_b32 s74, s40, s4
	v_lshl_add_u64 v[190:191], s[42:43], 0, v[136:137]
	s_add_i32 m0, s48, 0xc000
	ds_read_b128 v[174:177], v249
	ds_read_b128 v[178:181], v249 offset:1024
	ds_read_b128 v[182:185], v249 offset:2048
	ds_read_b128 v[186:189], v249 offset:3072
	ds_read_b128 v[194:197], v249 offset:4096
	ds_read_b128 v[198:201], v249 offset:5120
	ds_read_b128 v[202:205], v249 offset:6144
	ds_read_b128 v[206:209], v249 offset:7168
	global_load_lds_dwordx4 v[190:191], off
	v_lshl_add_u64 v[190:191], s[42:43], 0, v[138:139]
	s_add_i32 m0, s48, 0xe000
	s_nop 0
	global_load_lds_dwordx4 v[190:191], off
	s_waitcnt vmcnt(8)
	s_waitcnt lgkmcnt(0)
	s_barrier
	s_setprio 1
	s_waitcnt lgkmcnt(0)
	v_mfma_f32_16x16x32_bf16 v[124:127], v[142:145], v[174:177], v[124:127]
	v_mfma_f32_16x16x32_bf16 v[120:123], v[150:153], v[174:177], v[120:123]
	v_mfma_f32_16x16x32_bf16 v[116:119], v[142:145], v[182:185], v[116:119]
	v_mfma_f32_16x16x32_bf16 v[112:115], v[150:153], v[182:185], v[112:115]
	v_mfma_f32_16x16x32_bf16 v[104:107], v[142:145], v[194:197], v[104:107]
	v_mfma_f32_16x16x32_bf16 v[96:99], v[150:153], v[194:197], v[96:99]
	v_mfma_f32_16x16x32_bf16 v[88:91], v[142:145], v[202:205], v[88:91]
	v_mfma_f32_16x16x32_bf16 v[80:83], v[150:153], v[202:205], v[80:83]
	v_mfma_f32_16x16x32_bf16 v[124:127], v[146:149], v[178:181], v[124:127]
	v_mfma_f32_16x16x32_bf16 v[120:123], v[154:157], v[178:181], v[120:123]
	v_mfma_f32_16x16x32_bf16 v[116:119], v[146:149], v[186:189], v[116:119]
	v_mfma_f32_16x16x32_bf16 v[112:115], v[154:157], v[186:189], v[112:115]
	v_mfma_f32_16x16x32_bf16 v[104:107], v[146:149], v[198:201], v[104:107]
	v_mfma_f32_16x16x32_bf16 v[96:99], v[154:157], v[198:201], v[96:99]
	v_mfma_f32_16x16x32_bf16 v[88:91], v[146:149], v[206:209], v[88:91]
	v_mfma_f32_16x16x32_bf16 v[80:83], v[154:157], v[206:209], v[80:83]
	s_setprio 0
	s_setprio 1
	v_mfma_f32_16x16x32_bf16 v[108:111], v[158:161], v[174:177], v[108:111]
	v_mfma_f32_16x16x32_bf16 v[100:103], v[166:169], v[174:177], v[100:103]
	v_mfma_f32_16x16x32_bf16 v[92:95], v[158:161], v[182:185], v[92:95]
	v_mfma_f32_16x16x32_bf16 v[84:87], v[166:169], v[182:185], v[84:87]
	v_mfma_f32_16x16x32_bf16 v[76:79], v[158:161], v[194:197], v[76:79]
	v_mfma_f32_16x16x32_bf16 v[72:75], v[166:169], v[194:197], v[72:75]
	v_mfma_f32_16x16x32_bf16 v[68:71], v[158:161], v[202:205], v[68:71]
	v_mfma_f32_16x16x32_bf16 v[64:67], v[166:169], v[202:205], v[64:67]
	v_mfma_f32_16x16x32_bf16 v[108:111], v[162:165], v[178:181], v[108:111]
	v_mfma_f32_16x16x32_bf16 v[100:103], v[170:173], v[178:181], v[100:103]
	v_mfma_f32_16x16x32_bf16 v[92:95], v[162:165], v[186:189], v[92:95]
	v_mfma_f32_16x16x32_bf16 v[84:87], v[170:173], v[186:189], v[84:87]
	v_mfma_f32_16x16x32_bf16 v[76:79], v[162:165], v[198:201], v[76:79]
	v_mfma_f32_16x16x32_bf16 v[72:75], v[170:173], v[198:201], v[72:75]
	v_mfma_f32_16x16x32_bf16 v[68:71], v[162:165], v[206:209], v[68:71]
	v_mfma_f32_16x16x32_bf16 v[64:67], v[170:173], v[206:209], v[64:67]
	s_setprio 0
	s_barrier
; #define PG8_STAGE(bufoff, gbase, voff) do { _Pragma("unroll") for (int _i = 0; _i < 2; ++_i) \
;         __builtin_amdgcn_global_load_lds((const unsigned*)((const char*)(gbase) + (voff)[_i]), (PG8_LAS unsigned*)(lds + (bufoff) + ldsw + _i * 8192), 16, 0, 0); } while (0)
; #define PG8_LDA(dst, b, h) do { _Pragma("unroll") for (int m = 0; m < 4; ++m) _Pragma("unroll") for (int k = 0; k < 2; ++k) dst[m][k] = *(const PG8_LAS bf16x8*)(lds + PG8_SA(b, h) + aoff + m * 2048 + k * 1024); } while (0)
; #define PG8_LDB(dst, b, h) do { _Pragma("unroll") for (int n = 0; n < 2; ++n) _Pragma("unroll") for (int k = 0; k < 2; ++k) dst[n][k] = *(const PG8_LAS bf16x8*)(lds + PG8_SB(b, h) + boff + n * 2048 + k * 1024); } while (0)
; #define PG8_MMA(ai, bj, At, Bt) do { __builtin_amdgcn_s_setprio(1); _Pragma("unroll") for (int m = 0; m < 4; ++m) _Pragma("unroll") for (int n = 0; n < 2; ++n) _Pragma("unroll") for (int k = 0; k < 2; ++k) \
;         acc[ai][bj][m][n] = __builtin_amdgcn_mfma_f32_16x16x32_bf16(Bt[n][k], At[m][k], acc[ai][bj][m][n], 0, 0, 0); __builtin_amdgcn_s_setprio(0); } while (0)
; #define PG8_WAIT_V(n) asm volatile("s_waitcnt vmcnt(" #n ")" ::: "memory")
; #define PG8_WAIT_L(n) asm volatile("s_waitcnt lgkmcnt(" #n ")" ::: "memory")
; #define PG8_BAR __builtin_amdgcn_s_barrier()
; #define PG8_SCHED __builtin_amdgcn_sched_barrier(0)
; template <class Epi, class Sched, bool ALIGN_EPI = false, bool SP2 = false>
; __device__ __forceinline__ void gemm_phase(PG8_LAS unsigned char* lds, const Gemm g, const Sched& S, const Epi& E) {
;     ...
;             PG8_LDA(At, 0, 1); PG8_STAGE(PG8_SB(0, 0), b2, voffB); PG8_STAGE(PG8_SB(0, 1), b2 + hstep, voffB); PG8_STAGE(PG8_SA(0, 0), a2, voffA);
;             PG8_WAIT_V(8); PG8_WAIT_L(0); PG8_BAR; PG8_MMA(1, 0, At, B0); PG8_MMA(1, 1, At, B1); PG8_BAR; PG8_SCHED;
;             PG8_LDB(B0, 1, 0); PG8_LDB(B1, 1, 1); PG8_SCHED; PG8_LDA(At, 1, 0); PG8_STAGE(PG8_SA(0, 1), a2 + hstep, voffA);
	s_add_i32 s33, s66, s3
	v_lshl_add_u64 v[190:191], s[74:75], 0, v[130:131]
	s_mov_b32 m0, s33
	ds_read_b128 v[174:177], v249 offset:16384
	ds_read_b128 v[178:181], v249 offset:17408
	ds_read_b128 v[182:185], v249 offset:18432
	ds_read_b128 v[186:189], v249 offset:19456
	ds_read_b128 v[194:197], v249 offset:20480
	ds_read_b128 v[198:201], v249 offset:21504
	ds_read_b128 v[202:205], v249 offset:22528
	ds_read_b128 v[206:209], v249 offset:23552
	global_load_lds_dwordx4 v[190:191], off
	s_add_i32 m0, s33, 0x2000
	v_lshl_add_u64 v[210:211], s[74:75], 0, v[134:135]
	s_add_u32 s74, s74, s14
	s_addc_u32 s75, s75, s15
	s_add_i32 s33, s67, s3
	global_load_lds_dwordx4 v[210:211], off
	v_lshl_add_u64 v[212:213], s[74:75], 0, v[130:131]
	s_mov_b32 m0, s33
	v_lshl_add_u64 v[214:215], s[74:75], 0, v[134:135]
	global_load_lds_dwordx4 v[212:213], off
	s_add_i32 m0, s33, 0x2000
	v_lshl_add_u64 v[216:217], s[54:55], 0, v[128:129]
	global_load_lds_dwordx4 v[214:215], off
	s_mov_b32 m0, s48
	v_lshl_add_u64 v[218:219], s[54:55], 0, v[132:133]
	global_load_lds_dwordx4 v[216:217], off
	s_mov_b32 m0, s49
	s_nop 0
	global_load_lds_dwordx4 v[218:219], off
	s_waitcnt vmcnt(8)
	s_waitcnt lgkmcnt(0)
	s_barrier
	s_setprio 1
	s_waitcnt lgkmcnt(0)
	v_mfma_f32_16x16x32_bf16 v[60:63], v[142:145], v[174:177], v[60:63]
	v_mfma_f32_16x16x32_bf16 v[56:59], v[150:153], v[174:177], v[56:59]
	v_mfma_f32_16x16x32_bf16 v[52:55], v[142:145], v[182:185], v[52:55]
	v_mfma_f32_16x16x32_bf16 v[48:51], v[150:153], v[182:185], v[48:51]
	v_mfma_f32_16x16x32_bf16 v[40:43], v[142:145], v[194:197], v[40:43]
	v_mfma_f32_16x16x32_bf16 v[32:35], v[150:153], v[194:197], v[32:35]
	v_mfma_f32_16x16x32_bf16 v[24:27], v[142:145], v[202:205], v[24:27]
	v_mfma_f32_16x16x32_bf16 v[16:19], v[150:153], v[202:205], v[16:19]
	v_mfma_f32_16x16x32_bf16 v[60:63], v[146:149], v[178:181], v[60:63]
	v_mfma_f32_16x16x32_bf16 v[56:59], v[154:157], v[178:181], v[56:59]
	v_mfma_f32_16x16x32_bf16 v[52:55], v[146:149], v[186:189], v[52:55]
	v_mfma_f32_16x16x32_bf16 v[48:51], v[154:157], v[186:189], v[48:51]
	v_mfma_f32_16x16x32_bf16 v[40:43], v[146:149], v[198:201], v[40:43]
	v_mfma_f32_16x16x32_bf16 v[32:35], v[154:157], v[198:201], v[32:35]
	v_mfma_f32_16x16x32_bf16 v[24:27], v[146:149], v[206:209], v[24:27]
	v_mfma_f32_16x16x32_bf16 v[16:19], v[154:157], v[206:209], v[16:19]
	s_setprio 0
	s_setprio 1
	v_mfma_f32_16x16x32_bf16 v[44:47], v[158:161], v[174:177], v[44:47]
	v_mfma_f32_16x16x32_bf16 v[36:39], v[166:169], v[174:177], v[36:39]
	v_mfma_f32_16x16x32_bf16 v[28:31], v[158:161], v[182:185], v[28:31]
	v_mfma_f32_16x16x32_bf16 v[20:23], v[166:169], v[182:185], v[20:23]
	v_mfma_f32_16x16x32_bf16 v[12:15], v[158:161], v[194:197], v[12:15]
	v_mfma_f32_16x16x32_bf16 v[8:11], v[166:169], v[194:197], v[8:11]
	v_mfma_f32_16x16x32_bf16 v[4:7], v[158:161], v[202:205], v[4:7]
	v_mfma_f32_16x16x32_bf16 v[0:3], v[166:169], v[202:205], v[0:3]
	v_mfma_f32_16x16x32_bf16 v[44:47], v[162:165], v[178:181], v[44:47]
	v_mfma_f32_16x16x32_bf16 v[36:39], v[170:173], v[178:181], v[36:39]
	v_mfma_f32_16x16x32_bf16 v[28:31], v[162:165], v[186:189], v[28:31]
	v_mfma_f32_16x16x32_bf16 v[20:23], v[170:173], v[186:189], v[20:23]
	v_mfma_f32_16x16x32_bf16 v[12:15], v[162:165], v[198:201], v[12:15]
	v_mfma_f32_16x16x32_bf16 v[8:11], v[170:173], v[198:201], v[8:11]
	v_mfma_f32_16x16x32_bf16 v[4:7], v[162:165], v[206:209], v[4:7]
	v_mfma_f32_16x16x32_bf16 v[0:3], v[170:173], v[206:209], v[0:3]
	s_setprio 0
	s_barrier
	s_add_i32 s33, 0, 0x18000
	s_add_i32 s73, 0, 0x1c000
	v_add_u32_e32 v154, s33, v244
	v_add_u32_e32 v170, s73, v244
	ds_read_b128 v[142:145], v154
	ds_read_b128 v[146:149], v154 offset:1024
	ds_read_b128 v[150:153], v154 offset:2048
	ds_read_b128 v[154:157], v154 offset:3072
	ds_read_b128 v[158:161], v170
	ds_read_b128 v[162:165], v170 offset:1024
	ds_read_b128 v[166:169], v170 offset:2048
	ds_read_b128 v[170:173], v170 offset:3072
	s_add_u32 s54, s54, s14
	s_addc_u32 s55, s55, s15
	s_mov_b32 m0, s56
	v_lshl_add_u64 v[220:221], s[54:55], 0, v[128:129]
	ds_read_b128 v[174:177], v249 offset:32768
	ds_read_b128 v[178:181], v249 offset:33792
	ds_read_b128 v[182:185], v249 offset:34816
	ds_read_b128 v[186:189], v249 offset:35840
	ds_read_b128 v[194:197], v249 offset:36864
	ds_read_b128 v[198:201], v249 offset:37888
	ds_read_b128 v[202:205], v249 offset:38912
	ds_read_b128 v[206:209], v249 offset:39936
	global_load_lds_dwordx4 v[220:221], off
	v_lshl_add_u64 v[220:221], s[54:55], 0, v[132:133]
	s_mov_b32 m0, s57
	s_nop 0
	global_load_lds_dwordx4 v[220:221], off
	s_waitcnt vmcnt(8)
	s_waitcnt lgkmcnt(0)
	s_barrier
; #define PG8_STAGE(bufoff, gbase, voff) do { _Pragma("unroll") for (int _i = 0; _i < 2; ++_i) \
;         __builtin_amdgcn_global_load_lds((const unsigned*)((const char*)(gbase) + (voff)[_i]), (PG8_LAS unsigned*)(lds + (bufoff) + ldsw + _i * 8192), 16, 0, 0); } while (0)
; #define PG8_LDA(dst, b, h) do { _Pragma("unroll") for (int m = 0; m < 4; ++m) _Pragma("unroll") for (int k = 0; k < 2; ++k) dst[m][k] = *(const PG8_LAS bf16x8*)(lds + PG8_SA(b, h) + aoff + m * 2048 + k * 1024); } while (0)
; #define PG8_MMA(ai, bj, At, Bt) do { __builtin_amdgcn_s_setprio(1); _Pragma("unroll") for (int m = 0; m < 4; ++m) _Pragma("unroll") for (int n = 0; n < 2; ++n) _Pragma("unroll") for (int k = 0; k < 2; ++k) \
;         acc[ai][bj][m][n] = __builtin_amdgcn_mfma_f32_16x16x32_bf16(Bt[n][k], At[m][k], acc[ai][bj][m][n], 0, 0, 0); __builtin_amdgcn_s_setprio(0); } while (0)
; #define PG8_WAIT_V(n) asm volatile("s_waitcnt vmcnt(" #n ")" ::: "memory")
; #define PG8_WAIT_L(n) asm volatile("s_waitcnt lgkmcnt(" #n ")" ::: "memory")
; #define PG8_BAR __builtin_amdgcn_s_barrier()
; #define PG8_SCHED __builtin_amdgcn_sched_barrier(0)
; template <class Epi, class Sched, bool ALIGN_EPI = false, bool SP2 = false>
; __device__ __forceinline__ void gemm_phase(PG8_LAS unsigned char* lds, const Gemm g, const Sched& S, const Epi& E) {
;     ...
;         for (int t = 0; t < nt; t += 2) {
;             const bool last = (t == nt - 2);
;             const char* a1 = cA + (size_t)(t + 1) * kstep;
;             const char* a2 = last ? nA : cA + (size_t)(t + 2) * kstep; const char* b2 = last ? nB : cB + (size_t)(t + 2) * kstep;
;     ...
;             PG8_WAIT_V(8); PG8_WAIT_L(0); PG8_BAR; PG8_MMA(0, 0, At, B0); PG8_MMA(0, 1, At, B1); PG8_BAR; PG8_SCHED;
;             PG8_LDA(At, 1, 1); PG8_STAGE(PG8_SB(1, 0), b3, voffB); PG8_STAGE(PG8_SB(1, 1), b3 + hstep, voffB); PG8_STAGE(PG8_SA(1, 0), a3, voffA);
;             PG8_WAIT_V(8); PG8_WAIT_L(0); PG8_BAR; PG8_MMA(1, 0, At, B0); PG8_MMA(1, 1, At, B1); PG8_BAR; PG8_SCHED;
	s_setprio 1
	s_waitcnt lgkmcnt(0)
	v_mfma_f32_16x16x32_bf16 v[124:127], v[142:145], v[174:177], v[124:127]
	v_mfma_f32_16x16x32_bf16 v[120:123], v[150:153], v[174:177], v[120:123]
	v_mfma_f32_16x16x32_bf16 v[116:119], v[142:145], v[182:185], v[116:119]
	v_mfma_f32_16x16x32_bf16 v[112:115], v[150:153], v[182:185], v[112:115]
	v_mfma_f32_16x16x32_bf16 v[104:107], v[142:145], v[194:197], v[104:107]
	v_mfma_f32_16x16x32_bf16 v[96:99], v[150:153], v[194:197], v[96:99]
	v_mfma_f32_16x16x32_bf16 v[88:91], v[142:145], v[202:205], v[88:91]
	v_mfma_f32_16x16x32_bf16 v[80:83], v[150:153], v[202:205], v[80:83]
	v_mfma_f32_16x16x32_bf16 v[124:127], v[146:149], v[178:181], v[124:127]
	v_mfma_f32_16x16x32_bf16 v[120:123], v[154:157], v[178:181], v[120:123]
	v_mfma_f32_16x16x32_bf16 v[116:119], v[146:149], v[186:189], v[116:119]
	v_mfma_f32_16x16x32_bf16 v[112:115], v[154:157], v[186:189], v[112:115]
	v_mfma_f32_16x16x32_bf16 v[104:107], v[146:149], v[198:201], v[104:107]
	v_mfma_f32_16x16x32_bf16 v[96:99], v[154:157], v[198:201], v[96:99]
	v_mfma_f32_16x16x32_bf16 v[88:91], v[146:149], v[206:209], v[88:91]
	v_mfma_f32_16x16x32_bf16 v[80:83], v[154:157], v[206:209], v[80:83]
	s_setprio 0
	s_setprio 1
	v_mfma_f32_16x16x32_bf16 v[108:111], v[158:161], v[174:177], v[108:111]
	v_mfma_f32_16x16x32_bf16 v[100:103], v[166:169], v[174:177], v[100:103]
	v_mfma_f32_16x16x32_bf16 v[92:95], v[158:161], v[182:185], v[92:95]
	v_mfma_f32_16x16x32_bf16 v[84:87], v[166:169], v[182:185], v[84:87]
	v_mfma_f32_16x16x32_bf16 v[76:79], v[158:161], v[194:197], v[76:79]
	v_mfma_f32_16x16x32_bf16 v[72:75], v[166:169], v[194:197], v[72:75]
	v_mfma_f32_16x16x32_bf16 v[68:71], v[158:161], v[202:205], v[68:71]
	v_mfma_f32_16x16x32_bf16 v[64:67], v[166:169], v[202:205], v[64:67]
	v_mfma_f32_16x16x32_bf16 v[108:111], v[162:165], v[178:181], v[108:111]
	v_mfma_f32_16x16x32_bf16 v[100:103], v[170:173], v[178:181], v[100:103]
	v_mfma_f32_16x16x32_bf16 v[92:95], v[162:165], v[186:189], v[92:95]
	v_mfma_f32_16x16x32_bf16 v[84:87], v[170:173], v[186:189], v[84:87]
	v_mfma_f32_16x16x32_bf16 v[76:79], v[162:165], v[198:201], v[76:79]
	v_mfma_f32_16x16x32_bf16 v[72:75], v[170:173], v[198:201], v[72:75]
	v_mfma_f32_16x16x32_bf16 v[68:71], v[162:165], v[206:209], v[68:71]
	v_mfma_f32_16x16x32_bf16 v[64:67], v[170:173], v[206:209], v[64:67]
	s_setprio 0
	s_barrier
	s_add_i32 s33, s33, s3
	v_lshl_add_u64 v[190:191], v[190:191], 0, s[22:23]
	s_mov_b32 m0, s33
	ds_read_b128 v[174:177], v249 offset:49152
	ds_read_b128 v[178:181], v249 offset:50176
	ds_read_b128 v[182:185], v249 offset:51200
	ds_read_b128 v[186:189], v249 offset:52224
	ds_read_b128 v[194:197], v249 offset:53248
	ds_read_b128 v[198:201], v249 offset:54272
	ds_read_b128 v[202:205], v249 offset:55296
	ds_read_b128 v[206:209], v249 offset:56320
	global_load_lds_dwordx4 v[190:191], off
	v_lshl_add_u64 v[190:191], v[210:211], 0, s[22:23]
	s_add_i32 m0, s33, 0x2000
	s_add_i32 s33, s73, s3
	global_load_lds_dwordx4 v[190:191], off
	v_lshl_add_u64 v[190:191], v[212:213], 0, s[22:23]
	s_mov_b32 m0, s33
	s_nop 0
	global_load_lds_dwordx4 v[190:191], off
	v_lshl_add_u64 v[190:191], v[214:215], 0, s[22:23]
	s_add_i32 m0, s33, 0x2000
	s_nop 0
	global_load_lds_dwordx4 v[190:191], off
	v_lshl_add_u64 v[190:191], v[216:217], 0, s[22:23]
	s_mov_b32 m0, s58
	s_nop 0
	global_load_lds_dwordx4 v[190:191], off
	v_lshl_add_u64 v[190:191], v[218:219], 0, s[22:23]
	s_mov_b32 m0, s59
	s_nop 0
	global_load_lds_dwordx4 v[190:191], off
	s_waitcnt vmcnt(8)
	s_waitcnt lgkmcnt(0)
	s_barrier
	s_setprio 1
	s_waitcnt lgkmcnt(0)
	v_mfma_f32_16x16x32_bf16 v[60:63], v[142:145], v[174:177], v[60:63]
	v_mfma_f32_16x16x32_bf16 v[56:59], v[150:153], v[174:177], v[56:59]
	v_mfma_f32_16x16x32_bf16 v[52:55], v[142:145], v[182:185], v[52:55]
	v_mfma_f32_16x16x32_bf16 v[48:51], v[150:153], v[182:185], v[48:51]
	v_mfma_f32_16x16x32_bf16 v[40:43], v[142:145], v[194:197], v[40:43]
	v_mfma_f32_16x16x32_bf16 v[32:35], v[150:153], v[194:197], v[32:35]
	v_mfma_f32_16x16x32_bf16 v[24:27], v[142:145], v[202:205], v[24:27]
	v_mfma_f32_16x16x32_bf16 v[16:19], v[150:153], v[202:205], v[16:19]
	v_mfma_f32_16x16x32_bf16 v[60:63], v[146:149], v[178:181], v[60:63]
	v_mfma_f32_16x16x32_bf16 v[56:59], v[154:157], v[178:181], v[56:59]
	v_mfma_f32_16x16x32_bf16 v[52:55], v[146:149], v[186:189], v[52:55]
	v_mfma_f32_16x16x32_bf16 v[48:51], v[154:157], v[186:189], v[48:51]
	v_mfma_f32_16x16x32_bf16 v[40:43], v[146:149], v[198:201], v[40:43]
	v_mfma_f32_16x16x32_bf16 v[32:35], v[154:157], v[198:201], v[32:35]
	v_mfma_f32_16x16x32_bf16 v[24:27], v[146:149], v[206:209], v[24:27]
	v_mfma_f32_16x16x32_bf16 v[16:19], v[154:157], v[206:209], v[16:19]
	s_setprio 0
	s_setprio 1
	v_mfma_f32_16x16x32_bf16 v[44:47], v[158:161], v[174:177], v[44:47]
	v_mfma_f32_16x16x32_bf16 v[36:39], v[166:169], v[174:177], v[36:39]
	v_mfma_f32_16x16x32_bf16 v[28:31], v[158:161], v[182:185], v[28:31]
	v_mfma_f32_16x16x32_bf16 v[20:23], v[166:169], v[182:185], v[20:23]
	v_mfma_f32_16x16x32_bf16 v[12:15], v[158:161], v[194:197], v[12:15]
	v_mfma_f32_16x16x32_bf16 v[8:11], v[166:169], v[194:197], v[8:11]
	v_mfma_f32_16x16x32_bf16 v[4:7], v[158:161], v[202:205], v[4:7]
	v_mfma_f32_16x16x32_bf16 v[0:3], v[166:169], v[202:205], v[0:3]
	v_mfma_f32_16x16x32_bf16 v[44:47], v[162:165], v[178:181], v[44:47]
	v_mfma_f32_16x16x32_bf16 v[36:39], v[170:173], v[178:181], v[36:39]
	v_mfma_f32_16x16x32_bf16 v[28:31], v[162:165], v[186:189], v[28:31]
	v_mfma_f32_16x16x32_bf16 v[20:23], v[170:173], v[186:189], v[20:23]
	v_mfma_f32_16x16x32_bf16 v[12:15], v[162:165], v[198:201], v[12:15]
	v_mfma_f32_16x16x32_bf16 v[8:11], v[170:173], v[198:201], v[8:11]
	v_mfma_f32_16x16x32_bf16 v[4:7], v[162:165], v[206:209], v[4:7]
	v_mfma_f32_16x16x32_bf16 v[0:3], v[170:173], v[206:209], v[0:3]
	s_setprio 0
	s_barrier
	s_add_u32 s42, s42, 0x100
	s_addc_u32 s43, s43, 0
	s_add_u32 s4, s4, 0x100
	s_addc_u32 s5, s5, 0
	s_cmp_ge_i32 s72, s61
	s_mov_b32 s33, s72
	s_cbranch_scc0 .LBB0_1118
; #define PG8_BAR __builtin_amdgcn_s_barrier()
;     __device__ __forceinline__ void operator()(const f32x4 (&acc)[2][2][4][2], const Unit& u, int wr, int wc, int fr, int fq) const {
;         const int row0 = u.pm * BM + wr * 64 + fr, col0 = u.pn * BM + wc * 32 + 8 * fq;
;         u32x4 rb[2][4][2];
; #pragma unroll
;         for (int ai = 0; ai < 2; ++ai)
; #pragma unroll
;             for (int m = 0; m < 4; ++m) { const bf16_t* xq = XB + (size_t)(row0 + ai * HALF + m * 16) * 1024 + col0; rb[ai][m][0] = *(const u32x4*)xq; rb[ai][m][1] = *(const u32x4*)(xq + HALF); }
; #pragma unroll
;         for (int ai = 0; ai < 2; ++ai) {
; #pragma unroll
;             for (int m = 0; m < 4; ++m) {
;                 const int r = row0 + ai * HALF + m * 16;
;                 bf16_t* xp = XB + (size_t)r * 1024 + col0;
;                 const u32x4 b0 = rb[ai][m][0], b1 = rb[ai][m][1];
;                 float ss = 0.f;
; #pragma unroll
;                 for (int bj = 0; bj < 2; ++bj) {
;                     const u32x4 b = bj ? b1 : b0;
;                     f32x4 v0, v1;
;                     v0[0] = __uint_as_float(b.x << 16); v0[1] = __uint_as_float(b.x & 0xffff0000u); v0[2] = __uint_as_float(b.y << 16); v0[3] = __uint_as_float(b.y & 0xffff0000u);
;                     v1[0] = __uint_as_float(b.z << 16); v1[1] = __uint_as_float(b.z & 0xffff0000u); v1[2] = __uint_as_float(b.w << 16); v1[3] = __uint_as_float(b.w & 0xffff0000u);
;                     v0 += acc[ai][bj][m][0] * alpha; v1 += acc[ai][bj][m][1] * alpha;
;                     ss += (v0[0] * v0[0] + v0[1] * v0[1]) + (v0[2] * v0[2] + v0[3] * v0[3]) + (v1[0] * v1[0] + v1[1] * v1[1]) + (v1[2] * v1[2] + v1[3] * v1[3]);
;                     u32x4 w; w.x = cvt_pk_bf16(v0[0], v0[1]); w.y = cvt_pk_bf16(v0[2], v0[3]); w.z = cvt_pk_bf16(v1[0], v1[1]); w.w = cvt_pk_bf16(v1[2], v1[3]);
;                     *(u32x4*)(xp + bj * HALF) = w;
;                 }
;                 ss += __shfl_xor(ss, 16); ss += __shfl_xor(ss, 32);
;                 if (fq == 0) SS[(size_t)r * 16 + u.pn * 4 + wc] = ss;
; template <class Epi, class Sched, bool ALIGN_EPI = false, bool SP2 = false>
; __device__ __forceinline__ void gemm_phase(PG8_LAS unsigned char* lds, const Gemm g, const Sched& S, const Epi& E) {
;     ...
;         if constexpr (ALIGN_EPI) { if (wr == 0) PG8_BAR; }
.LBB0_1120:
	s_and_b64 vcc, exec, s[38:39]
	s_cbranch_vccz .LBB0_1122
	s_barrier
.LBB0_1122:
	v_lshl_or_b32 v142, s18, 8, v245
	v_lshl_add_u32 v144, s71, 8, v193
	v_lshlrev_b32_e32 v142, 1, v142
	v_mov_b32_e32 v143, 0
	v_mov_b32_e32 v145, 0
	s_mov_b32 s84, 0x8000
	s_mov_b32 s85, 0
	s_mov_b32 s86, 0x40000
	s_mov_b32 s87, 0
	v_lshl_add_u64 v[146:147], s[34:35], 0, v[142:143]
	v_lshlrev_b32_e32 v232, 11, v144
	v_mov_b32_e32 v233, 0
	v_lshl_add_u64 v[146:147], v[146:147], 0, v[232:233]
	v_lshl_add_u64 v[154:155], v[146:147], 0, s[86:87]
	v_lshl_add_u64 v[148:149], v[146:147], 0, s[84:85]
	v_lshl_add_u64 v[150:151], v[148:149], 0, s[84:85]
	v_lshl_add_u64 v[152:153], v[150:151], 0, s[84:85]
	v_lshl_add_u64 v[156:157], v[154:155], 0, s[84:85]
	v_lshl_add_u64 v[158:159], v[156:157], 0, s[84:85]
	v_lshl_add_u64 v[160:161], v[158:159], 0, s[84:85]
	global_load_dwordx4 v[164:167], v[146:147], off
	global_load_dwordx4 v[168:171], v[146:147], off offset:256
	global_load_dwordx4 v[172:175], v[148:149], off
	global_load_dwordx4 v[176:179], v[148:149], off offset:256
	global_load_dwordx4 v[180:183], v[150:151], off
	global_load_dwordx4 v[184:187], v[150:151], off offset:256
	global_load_dwordx4 v[188:191], v[152:153], off
	global_load_dwordx4 v[196:199], v[152:153], off offset:256
	global_load_dwordx4 v[200:203], v[154:155], off
	global_load_dwordx4 v[204:207], v[154:155], off offset:256
	global_load_dwordx4 v[208:211], v[156:157], off
	global_load_dwordx4 v[212:215], v[156:157], off offset:256
	global_load_dwordx4 v[216:219], v[158:159], off
	global_load_dwordx4 v[220:223], v[158:159], off offset:256
	global_load_dwordx4 v[224:227], v[160:161], off
	global_load_dwordx4 v[228:231], v[160:161], off offset:256
	v_xor_b32_e32 v194, 16, v246
	v_xor_b32_e32 v195, 32, v246
	v_lshlrev_b32_e32 v194, 2, v194
	v_lshlrev_b32_e32 v195, 2, v195
	s_lshl_b32 s90, s18, 2
	s_add_i32 s90, s90, s60
	s_lshl_b32 s90, s90, 2
	s_mov_b32 s91, 0
	v_lshlrev_b32_e32 v234, 6, v144
	v_mov_b32_e32 v235, 0
	v_lshl_add_u64 v[240:241], s[44:45], 0, v[234:235]
	v_lshl_add_u64 v[240:241], v[240:241], 0, s[90:91]
	s_waitcnt vmcnt(0)
	v_lshlrev_b32_e32 v232, 16, v164
	v_and_b32_e32 v233, 0xffff0000, v164
	v_lshlrev_b32_e32 v234, 16, v165
	v_and_b32_e32 v235, 0xffff0000, v165
	v_lshlrev_b32_e32 v236, 16, v166
	v_and_b32_e32 v237, 0xffff0000, v166
	v_lshlrev_b32_e32 v238, 16, v167
	v_and_b32_e32 v239, 0xffff0000, v167
	v_pk_fma_f32 v[124:125], v[124:125], 0.5, v[232:233] op_sel_hi:[1,0,1]
	v_pk_fma_f32 v[126:127], v[126:127], 0.5, v[234:235] op_sel_hi:[1,0,1]
	v_pk_fma_f32 v[120:121], v[120:121], 0.5, v[236:237] op_sel_hi:[1,0,1]
	v_pk_fma_f32 v[122:123], v[122:123], 0.5, v[238:239] op_sel_hi:[1,0,1]
	v_pk_mul_f32 v[162:163], v[124:125], v[124:125]
	v_pk_fma_f32 v[162:163], v[126:127], v[126:127], v[162:163]
	v_pk_fma_f32 v[162:163], v[120:121], v[120:121], v[162:163]
	v_pk_fma_f32 v[162:163], v[122:123], v[122:123], v[162:163]
	v_cvt_pk_bf16_f32 v164, v124, v125
	v_cvt_pk_bf16_f32 v165, v126, v127
	v_cvt_pk_bf16_f32 v166, v120, v121
	v_cvt_pk_bf16_f32 v167, v122, v123
	global_store_dwordx4 v[146:147], v[164:167], off
	v_lshlrev_b32_e32 v232, 16, v168
	v_and_b32_e32 v233, 0xffff0000, v168
	v_lshlrev_b32_e32 v234, 16, v169
	v_and_b32_e32 v235, 0xffff0000, v169
	v_lshlrev_b32_e32 v236, 16, v170
	v_and_b32_e32 v237, 0xffff0000, v170
	v_lshlrev_b32_e32 v238, 16, v171
	v_and_b32_e32 v239, 0xffff0000, v171
	v_pk_fma_f32 v[108:109], v[108:109], 0.5, v[232:233] op_sel_hi:[1,0,1]
	v_pk_fma_f32 v[110:111], v[110:111], 0.5, v[234:235] op_sel_hi:[1,0,1]
	v_pk_fma_f32 v[100:101], v[100:101], 0.5, v[236:237] op_sel_hi:[1,0,1]
	v_pk_fma_f32 v[102:103], v[102:103], 0.5, v[238:239] op_sel_hi:[1,0,1]
	v_pk_fma_f32 v[162:163], v[108:109], v[108:109], v[162:163]
	v_pk_fma_f32 v[162:163], v[110:111], v[110:111], v[162:163]
	v_pk_fma_f32 v[162:163], v[100:101], v[100:101], v[162:163]
	v_pk_fma_f32 v[162:163], v[102:103], v[102:103], v[162:163]
	v_cvt_pk_bf16_f32 v168, v108, v109
	v_cvt_pk_bf16_f32 v169, v110, v111
	v_cvt_pk_bf16_f32 v170, v100, v101
	v_cvt_pk_bf16_f32 v171, v102, v103
	global_store_dwordx4 v[146:147], v[168:171], off offset:256
	s_nop 0
	v_add_f32_e32 v146, v162, v163
	v_lshlrev_b32_e32 v232, 16, v172
	v_and_b32_e32 v233, 0xffff0000, v172
	v_lshlrev_b32_e32 v234, 16, v173
	v_and_b32_e32 v235, 0xffff0000, v173
	v_lshlrev_b32_e32 v236, 16, v174
	v_and_b32_e32 v237, 0xffff0000, v174
	v_lshlrev_b32_e32 v238, 16, v175
	v_and_b32_e32 v239, 0xffff0000, v175
	v_pk_fma_f32 v[116:117], v[116:117], 0.5, v[232:233] op_sel_hi:[1,0,1]
	v_pk_fma_f32 v[118:119], v[118:119], 0.5, v[234:235] op_sel_hi:[1,0,1]
	v_pk_fma_f32 v[112:113], v[112:113], 0.5, v[236:237] op_sel_hi:[1,0,1]
	v_pk_fma_f32 v[114:115], v[114:115], 0.5, v[238:239] op_sel_hi:[1,0,1]
	v_pk_mul_f32 v[162:163], v[116:117], v[116:117]
	v_pk_fma_f32 v[162:163], v[118:119], v[118:119], v[162:163]
	v_pk_fma_f32 v[162:163], v[112:113], v[112:113], v[162:163]
	v_pk_fma_f32 v[162:163], v[114:115], v[114:115], v[162:163]
	v_cvt_pk_bf16_f32 v172, v116, v117
	v_cvt_pk_bf16_f32 v173, v118, v119
	v_cvt_pk_bf16_f32 v174, v112, v113
	v_cvt_pk_bf16_f32 v175, v114, v115
	global_store_dwordx4 v[148:149], v[172:175], off
	v_lshlrev_b32_e32 v232, 16, v176
	v_and_b32_e32 v233, 0xffff0000, v176
	v_lshlrev_b32_e32 v234, 16, v177
	v_and_b32_e32 v235, 0xffff0000, v177
	v_lshlrev_b32_e32 v236, 16, v178
	v_and_b32_e32 v237, 0xffff0000, v178
	v_lshlrev_b32_e32 v238, 16, v179
	v_and_b32_e32 v239, 0xffff0000, v179
	v_pk_fma_f32 v[92:93], v[92:93], 0.5, v[232:233] op_sel_hi:[1,0,1]
	v_pk_fma_f32 v[94:95], v[94:95], 0.5, v[234:235] op_sel_hi:[1,0,1]
; __device__ __forceinline__ unsigned cvt_pk_bf16(float lo, float hi) { unsigned r; asm volatile("v_cvt_pk_bf16_f32 %0, %1, %2" : "=v"(r) : "v"(lo), "v"(hi)); return r; }
; __device__ __forceinline__ unsigned cvt_pk_bf16(float lo, float hi) { const f32x2 v = {lo, hi}; const bf16x2_t b = __builtin_convertvector(v, bf16x2_t); return __builtin_bit_cast(unsigned, b); }
;     __device__ __forceinline__ void operator()(const f32x4 (&acc)[2][2][4][2], const Unit& u, int wr, int wc, int fr, int fq) const {
;     ...
;                 const u32x4 b0 = rb[ai][m][0], b1 = rb[ai][m][1];
;                 float ss = 0.f;
; #pragma unroll
;                 for (int bj = 0; bj < 2; ++bj) {
;                     const u32x4 b = bj ? b1 : b0;
;                     f32x4 v0, v1;
;                     v0[0] = __uint_as_float(b.x << 16); v0[1] = __uint_as_float(b.x & 0xffff0000u); v0[2] = __uint_as_float(b.y << 16); v0[3] = __uint_as_float(b.y & 0xffff0000u);
;                     v1[0] = __uint_as_float(b.z << 16); v1[1] = __uint_as_float(b.z & 0xffff0000u); v1[2] = __uint_as_float(b.w << 16); v1[3] = __uint_as_float(b.w & 0xffff0000u);
;                     v0 += acc[ai][bj][m][0] * alpha; v1 += acc[ai][bj][m][1] * alpha;
;                     ss += (v0[0] * v0[0] + v0[1] * v0[1]) + (v0[2] * v0[2] + v0[3] * v0[3]) + (v1[0] * v1[0] + v1[1] * v1[1]) + (v1[2] * v1[2] + v1[3] * v1[3]);
;                     u32x4 w; w.x = cvt_pk_bf16(v0[0], v0[1]); w.y = cvt_pk_bf16(v0[2], v0[3]); w.z = cvt_pk_bf16(v1[0], v1[1]); w.w = cvt_pk_bf16(v1[2], v1[3]);
;                     *(u32x4*)(xp + bj * HALF) = w;
;                 }
	v_pk_fma_f32 v[84:85], v[84:85], 0.5, v[236:237] op_sel_hi:[1,0,1]
	v_pk_fma_f32 v[86:87], v[86:87], 0.5, v[238:239] op_sel_hi:[1,0,1]
	v_pk_fma_f32 v[162:163], v[92:93], v[92:93], v[162:163]
	v_pk_fma_f32 v[162:163], v[94:95], v[94:95], v[162:163]
	v_pk_fma_f32 v[162:163], v[84:85], v[84:85], v[162:163]
	v_pk_fma_f32 v[162:163], v[86:87], v[86:87], v[162:163]
	v_cvt_pk_bf16_f32 v176, v92, v93
	v_cvt_pk_bf16_f32 v177, v94, v95
	v_cvt_pk_bf16_f32 v178, v84, v85
	v_cvt_pk_bf16_f32 v179, v86, v87
	global_store_dwordx4 v[148:149], v[176:179], off offset:256
	s_nop 0
	v_add_f32_e32 v148, v162, v163
	v_lshlrev_b32_e32 v232, 16, v180
	v_and_b32_e32 v233, 0xffff0000, v180
	v_lshlrev_b32_e32 v234, 16, v181
	v_and_b32_e32 v235, 0xffff0000, v181
	v_lshlrev_b32_e32 v236, 16, v182
	v_and_b32_e32 v237, 0xffff0000, v182
	v_lshlrev_b32_e32 v238, 16, v183
	v_and_b32_e32 v239, 0xffff0000, v183
	v_pk_fma_f32 v[104:105], v[104:105], 0.5, v[232:233] op_sel_hi:[1,0,1]
	v_pk_fma_f32 v[106:107], v[106:107], 0.5, v[234:235] op_sel_hi:[1,0,1]
	v_pk_fma_f32 v[96:97], v[96:97], 0.5, v[236:237] op_sel_hi:[1,0,1]
	v_pk_fma_f32 v[98:99], v[98:99], 0.5, v[238:239] op_sel_hi:[1,0,1]
	v_pk_mul_f32 v[162:163], v[104:105], v[104:105]
	v_pk_fma_f32 v[162:163], v[106:107], v[106:107], v[162:163]
	v_pk_fma_f32 v[162:163], v[96:97], v[96:97], v[162:163]
	v_pk_fma_f32 v[162:163], v[98:99], v[98:99], v[162:163]
	v_cvt_pk_bf16_f32 v180, v104, v105
	v_cvt_pk_bf16_f32 v181, v106, v107
	v_cvt_pk_bf16_f32 v182, v96, v97
	v_cvt_pk_bf16_f32 v183, v98, v99
	global_store_dwordx4 v[150:151], v[180:183], off
	v_lshlrev_b32_e32 v232, 16, v184
	v_and_b32_e32 v233, 0xffff0000, v184
	v_lshlrev_b32_e32 v234, 16, v185
	v_and_b32_e32 v235, 0xffff0000, v185
	v_lshlrev_b32_e32 v236, 16, v186
	v_and_b32_e32 v237, 0xffff0000, v186
	v_lshlrev_b32_e32 v238, 16, v187
	v_and_b32_e32 v239, 0xffff0000, v187
	v_pk_fma_f32 v[76:77], v[76:77], 0.5, v[232:233] op_sel_hi:[1,0,1]
	v_pk_fma_f32 v[78:79], v[78:79], 0.5, v[234:235] op_sel_hi:[1,0,1]
	v_pk_fma_f32 v[72:73], v[72:73], 0.5, v[236:237] op_sel_hi:[1,0,1]
	v_pk_fma_f32 v[74:75], v[74:75], 0.5, v[238:239] op_sel_hi:[1,0,1]
	v_pk_fma_f32 v[162:163], v[76:77], v[76:77], v[162:163]
	v_pk_fma_f32 v[162:163], v[78:79], v[78:79], v[162:163]
	v_pk_fma_f32 v[162:163], v[72:73], v[72:73], v[162:163]
	v_pk_fma_f32 v[162:163], v[74:75], v[74:75], v[162:163]
	v_cvt_pk_bf16_f32 v184, v76, v77
	v_cvt_pk_bf16_f32 v185, v78, v79
	v_cvt_pk_bf16_f32 v186, v72, v73
	v_cvt_pk_bf16_f32 v187, v74, v75
	global_store_dwordx4 v[150:151], v[184:187], off offset:256
	s_nop 0
	v_add_f32_e32 v150, v162, v163
	v_lshlrev_b32_e32 v232, 16, v188
	v_and_b32_e32 v233, 0xffff0000, v188
	v_lshlrev_b32_e32 v234, 16, v189
	v_and_b32_e32 v235, 0xffff0000, v189
	v_lshlrev_b32_e32 v236, 16, v190
	v_and_b32_e32 v237, 0xffff0000, v190
	v_lshlrev_b32_e32 v238, 16, v191
	v_and_b32_e32 v239, 0xffff0000, v191
	v_pk_fma_f32 v[88:89], v[88:89], 0.5, v[232:233] op_sel_hi:[1,0,1]
	v_pk_fma_f32 v[90:91], v[90:91], 0.5, v[234:235] op_sel_hi:[1,0,1]
	v_pk_fma_f32 v[80:81], v[80:81], 0.5, v[236:237] op_sel_hi:[1,0,1]
	v_pk_fma_f32 v[82:83], v[82:83], 0.5, v[238:239] op_sel_hi:[1,0,1]
	v_pk_mul_f32 v[162:163], v[88:89], v[88:89]
	v_pk_fma_f32 v[162:163], v[90:91], v[90:91], v[162:163]
	v_pk_fma_f32 v[162:163], v[80:81], v[80:81], v[162:163]
	v_pk_fma_f32 v[162:163], v[82:83], v[82:83], v[162:163]
	v_cvt_pk_bf16_f32 v188, v88, v89
	v_cvt_pk_bf16_f32 v189, v90, v91
	v_cvt_pk_bf16_f32 v190, v80, v81
	v_cvt_pk_bf16_f32 v191, v82, v83
	global_store_dwordx4 v[152:153], v[188:191], off
	v_lshlrev_b32_e32 v232, 16, v196
	v_and_b32_e32 v233, 0xffff0000, v196
	v_lshlrev_b32_e32 v234, 16, v197
	v_and_b32_e32 v235, 0xffff0000, v197
	v_lshlrev_b32_e32 v236, 16, v198
	v_and_b32_e32 v237, 0xffff0000, v198
	v_lshlrev_b32_e32 v238, 16, v199
	v_and_b32_e32 v239, 0xffff0000, v199
	v_pk_fma_f32 v[68:69], v[68:69], 0.5, v[232:233] op_sel_hi:[1,0,1]
	v_pk_fma_f32 v[70:71], v[70:71], 0.5, v[234:235] op_sel_hi:[1,0,1]
	v_pk_fma_f32 v[64:65], v[64:65], 0.5, v[236:237] op_sel_hi:[1,0,1]
	v_pk_fma_f32 v[66:67], v[66:67], 0.5, v[238:239] op_sel_hi:[1,0,1]
	v_pk_fma_f32 v[162:163], v[68:69], v[68:69], v[162:163]
	v_pk_fma_f32 v[162:163], v[70:71], v[70:71], v[162:163]
	v_pk_fma_f32 v[162:163], v[64:65], v[64:65], v[162:163]
	v_pk_fma_f32 v[162:163], v[66:67], v[66:67], v[162:163]
	v_cvt_pk_bf16_f32 v196, v68, v69
	v_cvt_pk_bf16_f32 v197, v70, v71
	v_cvt_pk_bf16_f32 v198, v64, v65
	v_cvt_pk_bf16_f32 v199, v66, v67
	global_store_dwordx4 v[152:153], v[196:199], off offset:256
	s_nop 0
	v_add_f32_e32 v152, v162, v163
	v_lshlrev_b32_e32 v232, 16, v200
	v_and_b32_e32 v233, 0xffff0000, v200
	v_lshlrev_b32_e32 v234, 16, v201
	v_and_b32_e32 v235, 0xffff0000, v201
	v_lshlrev_b32_e32 v236, 16, v202
	v_and_b32_e32 v237, 0xffff0000, v202
	v_lshlrev_b32_e32 v238, 16, v203
	v_and_b32_e32 v239, 0xffff0000, v203
	v_pk_fma_f32 v[60:61], v[60:61], 0.5, v[232:233] op_sel_hi:[1,0,1]
	v_pk_fma_f32 v[62:63], v[62:63], 0.5, v[234:235] op_sel_hi:[1,0,1]
	v_pk_fma_f32 v[56:57], v[56:57], 0.5, v[236:237] op_sel_hi:[1,0,1]
	v_pk_fma_f32 v[58:59], v[58:59], 0.5, v[238:239] op_sel_hi:[1,0,1]
	v_pk_mul_f32 v[162:163], v[60:61], v[60:61]
	v_pk_fma_f32 v[162:163], v[62:63], v[62:63], v[162:163]
	v_pk_fma_f32 v[162:163], v[56:57], v[56:57], v[162:163]
	v_pk_fma_f32 v[162:163], v[58:59], v[58:59], v[162:163]
	v_cvt_pk_bf16_f32 v200, v60, v61
	v_cvt_pk_bf16_f32 v201, v62, v63
	v_cvt_pk_bf16_f32 v202, v56, v57
	v_cvt_pk_bf16_f32 v203, v58, v59
	global_store_dwordx4 v[154:155], v[200:203], off
	v_lshlrev_b32_e32 v232, 16, v204
	v_and_b32_e32 v233, 0xffff0000, v204
; __device__ __forceinline__ unsigned cvt_pk_bf16(float lo, float hi) { unsigned r; asm volatile("v_cvt_pk_bf16_f32 %0, %1, %2" : "=v"(r) : "v"(lo), "v"(hi)); return r; }
; __device__ __forceinline__ unsigned cvt_pk_bf16(float lo, float hi) { const f32x2 v = {lo, hi}; const bf16x2_t b = __builtin_convertvector(v, bf16x2_t); return __builtin_bit_cast(unsigned, b); }
;     __device__ __forceinline__ void operator()(const f32x4 (&acc)[2][2][4][2], const Unit& u, int wr, int wc, int fr, int fq) const {
;     ...
;                 const u32x4 b0 = rb[ai][m][0], b1 = rb[ai][m][1];
;                 float ss = 0.f;
; #pragma unroll
;                 for (int bj = 0; bj < 2; ++bj) {
;                     const u32x4 b = bj ? b1 : b0;
;                     f32x4 v0, v1;
;                     v0[0] = __uint_as_float(b.x << 16); v0[1] = __uint_as_float(b.x & 0xffff0000u); v0[2] = __uint_as_float(b.y << 16); v0[3] = __uint_as_float(b.y & 0xffff0000u);
;                     v1[0] = __uint_as_float(b.z << 16); v1[1] = __uint_as_float(b.z & 0xffff0000u); v1[2] = __uint_as_float(b.w << 16); v1[3] = __uint_as_float(b.w & 0xffff0000u);
;                     v0 += acc[ai][bj][m][0] * alpha; v1 += acc[ai][bj][m][1] * alpha;
;                     ss += (v0[0] * v0[0] + v0[1] * v0[1]) + (v0[2] * v0[2] + v0[3] * v0[3]) + (v1[0] * v1[0] + v1[1] * v1[1]) + (v1[2] * v1[2] + v1[3] * v1[3]);
;                     u32x4 w; w.x = cvt_pk_bf16(v0[0], v0[1]); w.y = cvt_pk_bf16(v0[2], v0[3]); w.z = cvt_pk_bf16(v1[0], v1[1]); w.w = cvt_pk_bf16(v1[2], v1[3]);
;                     *(u32x4*)(xp + bj * HALF) = w;
;                 }
	v_lshlrev_b32_e32 v234, 16, v205
	v_and_b32_e32 v235, 0xffff0000, v205
	v_lshlrev_b32_e32 v236, 16, v206
	v_and_b32_e32 v237, 0xffff0000, v206
	v_lshlrev_b32_e32 v238, 16, v207
	v_and_b32_e32 v239, 0xffff0000, v207
	v_pk_fma_f32 v[44:45], v[44:45], 0.5, v[232:233] op_sel_hi:[1,0,1]
	v_pk_fma_f32 v[46:47], v[46:47], 0.5, v[234:235] op_sel_hi:[1,0,1]
	v_pk_fma_f32 v[36:37], v[36:37], 0.5, v[236:237] op_sel_hi:[1,0,1]
	v_pk_fma_f32 v[38:39], v[38:39], 0.5, v[238:239] op_sel_hi:[1,0,1]
	v_pk_fma_f32 v[162:163], v[44:45], v[44:45], v[162:163]
	v_pk_fma_f32 v[162:163], v[46:47], v[46:47], v[162:163]
	v_pk_fma_f32 v[162:163], v[36:37], v[36:37], v[162:163]
	v_pk_fma_f32 v[162:163], v[38:39], v[38:39], v[162:163]
	v_cvt_pk_bf16_f32 v204, v44, v45
	v_cvt_pk_bf16_f32 v205, v46, v47
	v_cvt_pk_bf16_f32 v206, v36, v37
	v_cvt_pk_bf16_f32 v207, v38, v39
	global_store_dwordx4 v[154:155], v[204:207], off offset:256
	s_nop 0
	v_add_f32_e32 v154, v162, v163
	v_lshlrev_b32_e32 v232, 16, v208
	v_and_b32_e32 v233, 0xffff0000, v208
	v_lshlrev_b32_e32 v234, 16, v209
	v_and_b32_e32 v235, 0xffff0000, v209
	v_lshlrev_b32_e32 v236, 16, v210
	v_and_b32_e32 v237, 0xffff0000, v210
	v_lshlrev_b32_e32 v238, 16, v211
	v_and_b32_e32 v239, 0xffff0000, v211
	v_pk_fma_f32 v[52:53], v[52:53], 0.5, v[232:233] op_sel_hi:[1,0,1]
	v_pk_fma_f32 v[54:55], v[54:55], 0.5, v[234:235] op_sel_hi:[1,0,1]
	v_pk_fma_f32 v[48:49], v[48:49], 0.5, v[236:237] op_sel_hi:[1,0,1]
	v_pk_fma_f32 v[50:51], v[50:51], 0.5, v[238:239] op_sel_hi:[1,0,1]
	v_pk_mul_f32 v[162:163], v[52:53], v[52:53]
	v_pk_fma_f32 v[162:163], v[54:55], v[54:55], v[162:163]
	v_pk_fma_f32 v[162:163], v[48:49], v[48:49], v[162:163]
	v_pk_fma_f32 v[162:163], v[50:51], v[50:51], v[162:163]
	v_cvt_pk_bf16_f32 v208, v52, v53
	v_cvt_pk_bf16_f32 v209, v54, v55
	v_cvt_pk_bf16_f32 v210, v48, v49
	v_cvt_pk_bf16_f32 v211, v50, v51
	global_store_dwordx4 v[156:157], v[208:211], off
	v_lshlrev_b32_e32 v232, 16, v212
	v_and_b32_e32 v233, 0xffff0000, v212
	v_lshlrev_b32_e32 v234, 16, v213
	v_and_b32_e32 v235, 0xffff0000, v213
	v_lshlrev_b32_e32 v236, 16, v214
	v_and_b32_e32 v237, 0xffff0000, v214
	v_lshlrev_b32_e32 v238, 16, v215
	v_and_b32_e32 v239, 0xffff0000, v215
	v_pk_fma_f32 v[28:29], v[28:29], 0.5, v[232:233] op_sel_hi:[1,0,1]
	v_pk_fma_f32 v[30:31], v[30:31], 0.5, v[234:235] op_sel_hi:[1,0,1]
	v_pk_fma_f32 v[20:21], v[20:21], 0.5, v[236:237] op_sel_hi:[1,0,1]
	v_pk_fma_f32 v[22:23], v[22:23], 0.5, v[238:239] op_sel_hi:[1,0,1]
	v_pk_fma_f32 v[162:163], v[28:29], v[28:29], v[162:163]
	v_pk_fma_f32 v[162:163], v[30:31], v[30:31], v[162:163]
	v_pk_fma_f32 v[162:163], v[20:21], v[20:21], v[162:163]
	v_pk_fma_f32 v[162:163], v[22:23], v[22:23], v[162:163]
	v_cvt_pk_bf16_f32 v212, v28, v29
	v_cvt_pk_bf16_f32 v213, v30, v31
	v_cvt_pk_bf16_f32 v214, v20, v21
	v_cvt_pk_bf16_f32 v215, v22, v23
	global_store_dwordx4 v[156:157], v[212:215], off offset:256
	s_nop 0
	v_add_f32_e32 v156, v162, v163
	v_lshlrev_b32_e32 v232, 16, v216
	v_and_b32_e32 v233, 0xffff0000, v216
	v_lshlrev_b32_e32 v234, 16, v217
	v_and_b32_e32 v235, 0xffff0000, v217
	v_lshlrev_b32_e32 v236, 16, v218
	v_and_b32_e32 v237, 0xffff0000, v218
	v_lshlrev_b32_e32 v238, 16, v219
	v_and_b32_e32 v239, 0xffff0000, v219
	v_pk_fma_f32 v[40:41], v[40:41], 0.5, v[232:233] op_sel_hi:[1,0,1]
	v_pk_fma_f32 v[42:43], v[42:43], 0.5, v[234:235] op_sel_hi:[1,0,1]
	v_pk_fma_f32 v[32:33], v[32:33], 0.5, v[236:237] op_sel_hi:[1,0,1]
	v_pk_fma_f32 v[34:35], v[34:35], 0.5, v[238:239] op_sel_hi:[1,0,1]
	v_pk_mul_f32 v[162:163], v[40:41], v[40:41]
	v_pk_fma_f32 v[162:163], v[42:43], v[42:43], v[162:163]
	v_pk_fma_f32 v[162:163], v[32:33], v[32:33], v[162:163]
	v_pk_fma_f32 v[162:163], v[34:35], v[34:35], v[162:163]
	v_cvt_pk_bf16_f32 v216, v40, v41
	v_cvt_pk_bf16_f32 v217, v42, v43
	v_cvt_pk_bf16_f32 v218, v32, v33
	v_cvt_pk_bf16_f32 v219, v34, v35
	global_store_dwordx4 v[158:159], v[216:219], off
	v_lshlrev_b32_e32 v232, 16, v220
	v_and_b32_e32 v233, 0xffff0000, v220
	v_lshlrev_b32_e32 v234, 16, v221
	v_and_b32_e32 v235, 0xffff0000, v221
	v_lshlrev_b32_e32 v236, 16, v222
	v_and_b32_e32 v237, 0xffff0000, v222
	v_lshlrev_b32_e32 v238, 16, v223
	v_and_b32_e32 v239, 0xffff0000, v223
	v_pk_fma_f32 v[12:13], v[12:13], 0.5, v[232:233] op_sel_hi:[1,0,1]
	v_pk_fma_f32 v[14:15], v[14:15], 0.5, v[234:235] op_sel_hi:[1,0,1]
	v_pk_fma_f32 v[8:9], v[8:9], 0.5, v[236:237] op_sel_hi:[1,0,1]
	v_pk_fma_f32 v[10:11], v[10:11], 0.5, v[238:239] op_sel_hi:[1,0,1]
	v_pk_fma_f32 v[162:163], v[12:13], v[12:13], v[162:163]
; __device__ __forceinline__ unsigned cvt_pk_bf16(float lo, float hi) { unsigned r; asm volatile("v_cvt_pk_bf16_f32 %0, %1, %2" : "=v"(r) : "v"(lo), "v"(hi)); return r; }
; #define PG8_BAR __builtin_amdgcn_s_barrier()
; __device__ __forceinline__ unsigned cvt_pk_bf16(float lo, float hi) { const f32x2 v = {lo, hi}; const bf16x2_t b = __builtin_convertvector(v, bf16x2_t); return __builtin_bit_cast(unsigned, b); }
;     __device__ __forceinline__ void operator()(const f32x4 (&acc)[2][2][4][2], const Unit& u, int wr, int wc, int fr, int fq) const {
;     ...
;                 for (int bj = 0; bj < 2; ++bj) {
;                     const u32x4 b = bj ? b1 : b0;
;                     f32x4 v0, v1;
;                     v0[0] = __uint_as_float(b.x << 16); v0[1] = __uint_as_float(b.x & 0xffff0000u); v0[2] = __uint_as_float(b.y << 16); v0[3] = __uint_as_float(b.y & 0xffff0000u);
;                     v1[0] = __uint_as_float(b.z << 16); v1[1] = __uint_as_float(b.z & 0xffff0000u); v1[2] = __uint_as_float(b.w << 16); v1[3] = __uint_as_float(b.w & 0xffff0000u);
;                     v0 += acc[ai][bj][m][0] * alpha; v1 += acc[ai][bj][m][1] * alpha;
;                     ss += (v0[0] * v0[0] + v0[1] * v0[1]) + (v0[2] * v0[2] + v0[3] * v0[3]) + (v1[0] * v1[0] + v1[1] * v1[1]) + (v1[2] * v1[2] + v1[3] * v1[3]);
;                     u32x4 w; w.x = cvt_pk_bf16(v0[0], v0[1]); w.y = cvt_pk_bf16(v0[2], v0[3]); w.z = cvt_pk_bf16(v1[0], v1[1]); w.w = cvt_pk_bf16(v1[2], v1[3]);
;                     *(u32x4*)(xp + bj * HALF) = w;
;                 }
;                 ss += __shfl_xor(ss, 16); ss += __shfl_xor(ss, 32);
;                 if (fq == 0) SS[(size_t)r * 16 + u.pn * 4 + wc] = ss;
; template <class Epi, class Sched, bool ALIGN_EPI = false, bool SP2 = false>
; __device__ __forceinline__ void gemm_phase(PG8_LAS unsigned char* lds, const Gemm g, const Sched& S, const Epi& E) {
;     ...
;         if constexpr (!Epi::AFTER_DRAIN) { E(acc, cur, wr, wc, fr, fq); S.done(cur); }
;         if (!has_next) break;
; #pragma unroll
;         for (int a = 0; a < 2; ++a)
; #pragma unroll
;             for (int b = 0; b < 2; ++b)
; #pragma unroll
;                 for (int m = 0; m < 4; ++m)
; #pragma unroll
;                     for (int n = 0; n < 2; ++n) acc[a][b][m][n] = (f32x4){0.f, 0.f, 0.f, 0.f};
;         cur = nxt; cA = nA; cB = nB; ++ui;
;         if constexpr (ALIGN_EPI) { if (wr == 1) PG8_BAR; }
	v_pk_fma_f32 v[162:163], v[14:15], v[14:15], v[162:163]
	v_pk_fma_f32 v[162:163], v[8:9], v[8:9], v[162:163]
	v_pk_fma_f32 v[162:163], v[10:11], v[10:11], v[162:163]
	v_cvt_pk_bf16_f32 v220, v12, v13
	v_cvt_pk_bf16_f32 v221, v14, v15
	v_cvt_pk_bf16_f32 v222, v8, v9
	v_cvt_pk_bf16_f32 v223, v10, v11
	global_store_dwordx4 v[158:159], v[220:223], off offset:256
	s_nop 0
	v_add_f32_e32 v158, v162, v163
	v_lshlrev_b32_e32 v232, 16, v224
	v_and_b32_e32 v233, 0xffff0000, v224
	v_lshlrev_b32_e32 v234, 16, v225
	v_and_b32_e32 v235, 0xffff0000, v225
	v_lshlrev_b32_e32 v236, 16, v226
	v_and_b32_e32 v237, 0xffff0000, v226
	v_lshlrev_b32_e32 v238, 16, v227
	v_and_b32_e32 v239, 0xffff0000, v227
	v_pk_fma_f32 v[24:25], v[24:25], 0.5, v[232:233] op_sel_hi:[1,0,1]
	v_pk_fma_f32 v[26:27], v[26:27], 0.5, v[234:235] op_sel_hi:[1,0,1]
	v_pk_fma_f32 v[16:17], v[16:17], 0.5, v[236:237] op_sel_hi:[1,0,1]
	v_pk_fma_f32 v[18:19], v[18:19], 0.5, v[238:239] op_sel_hi:[1,0,1]
	v_pk_mul_f32 v[162:163], v[24:25], v[24:25]
	v_pk_fma_f32 v[162:163], v[26:27], v[26:27], v[162:163]
	v_pk_fma_f32 v[162:163], v[16:17], v[16:17], v[162:163]
	v_pk_fma_f32 v[162:163], v[18:19], v[18:19], v[162:163]
	v_cvt_pk_bf16_f32 v224, v24, v25
	v_cvt_pk_bf16_f32 v225, v26, v27
	v_cvt_pk_bf16_f32 v226, v16, v17
	v_cvt_pk_bf16_f32 v227, v18, v19
	global_store_dwordx4 v[160:161], v[224:227], off
	v_lshlrev_b32_e32 v232, 16, v228
	v_and_b32_e32 v233, 0xffff0000, v228
	v_lshlrev_b32_e32 v234, 16, v229
	v_and_b32_e32 v235, 0xffff0000, v229
	v_lshlrev_b32_e32 v236, 16, v230
	v_and_b32_e32 v237, 0xffff0000, v230
	v_lshlrev_b32_e32 v238, 16, v231
	v_and_b32_e32 v239, 0xffff0000, v231
	v_pk_fma_f32 v[4:5], v[4:5], 0.5, v[232:233] op_sel_hi:[1,0,1]
	v_pk_fma_f32 v[6:7], v[6:7], 0.5, v[234:235] op_sel_hi:[1,0,1]
	v_pk_fma_f32 v[0:1], v[0:1], 0.5, v[236:237] op_sel_hi:[1,0,1]
	v_pk_fma_f32 v[2:3], v[2:3], 0.5, v[238:239] op_sel_hi:[1,0,1]
	v_pk_fma_f32 v[162:163], v[4:5], v[4:5], v[162:163]
	v_pk_fma_f32 v[162:163], v[6:7], v[6:7], v[162:163]
	v_pk_fma_f32 v[162:163], v[0:1], v[0:1], v[162:163]
	v_pk_fma_f32 v[162:163], v[2:3], v[2:3], v[162:163]
	v_cvt_pk_bf16_f32 v228, v4, v5
	v_cvt_pk_bf16_f32 v229, v6, v7
	v_cvt_pk_bf16_f32 v230, v0, v1
	v_cvt_pk_bf16_f32 v231, v2, v3
	global_store_dwordx4 v[160:161], v[228:231], off offset:256
	s_nop 0
	v_add_f32_e32 v160, v162, v163
	ds_bpermute_b32 v147, v194, v146
	ds_bpermute_b32 v149, v194, v148
	ds_bpermute_b32 v151, v194, v150
	ds_bpermute_b32 v153, v194, v152
	ds_bpermute_b32 v155, v194, v154
	ds_bpermute_b32 v157, v194, v156
	ds_bpermute_b32 v159, v194, v158
	ds_bpermute_b32 v161, v194, v160
	s_waitcnt lgkmcnt(7)
	v_add_f32_e32 v146, v146, v147
	s_waitcnt lgkmcnt(6)
	v_add_f32_e32 v148, v148, v149
	s_waitcnt lgkmcnt(5)
	v_add_f32_e32 v150, v150, v151
	s_waitcnt lgkmcnt(4)
	v_add_f32_e32 v152, v152, v153
	s_waitcnt lgkmcnt(3)
	v_add_f32_e32 v154, v154, v155
	s_waitcnt lgkmcnt(2)
	v_add_f32_e32 v156, v156, v157
	s_waitcnt lgkmcnt(1)
	v_add_f32_e32 v158, v158, v159
	s_waitcnt lgkmcnt(0)
	v_add_f32_e32 v160, v160, v161
	ds_bpermute_b32 v147, v195, v146
	ds_bpermute_b32 v149, v195, v148
	ds_bpermute_b32 v151, v195, v150
	ds_bpermute_b32 v153, v195, v152
	ds_bpermute_b32 v155, v195, v154
	ds_bpermute_b32 v157, v195, v156
	ds_bpermute_b32 v159, v195, v158
	ds_bpermute_b32 v161, v195, v160
	s_waitcnt lgkmcnt(7)
	v_add_f32_e32 v146, v146, v147
	s_waitcnt lgkmcnt(6)
	v_add_f32_e32 v148, v148, v149
	s_waitcnt lgkmcnt(5)
	v_add_f32_e32 v150, v150, v151
	s_waitcnt lgkmcnt(4)
	v_add_f32_e32 v152, v152, v153
	s_waitcnt lgkmcnt(3)
	v_add_f32_e32 v154, v154, v155
	s_waitcnt lgkmcnt(2)
	v_add_f32_e32 v156, v156, v157
	s_waitcnt lgkmcnt(1)
	v_add_f32_e32 v158, v158, v159
	s_waitcnt lgkmcnt(0)
	v_add_f32_e32 v160, v160, v161
	s_and_saveexec_b64 s[88:89], s[0:1]
	global_store_dword v[240:241], v146, off
	global_store_dword v[240:241], v148, off offset:1024
	global_store_dword v[240:241], v150, off offset:2048
	global_store_dword v[240:241], v152, off offset:3072
	s_movk_i32 s84, 0x2000
	v_lshl_add_u64 v[240:241], v[240:241], 0, s[84:85]
	global_store_dword v[240:241], v154, off
	global_store_dword v[240:241], v156, off offset:1024
	global_store_dword v[240:241], v158, off offset:2048
	global_store_dword v[240:241], v160, off offset:3072
	s_or_b64 exec, exec, s[88:89]
	v_and_b32_e32 v56, 64, v246
	v_add_u32_e32 v56, 64, v56
	s_and_b64 vcc, exec, s[6:7]
	s_mov_b64 s[6:7], -1
	s_cbranch_vccnz .LBB0_1105
	s_andn2_b64 vcc, exec, s[20:21]
	s_cbranch_vccnz .LBB0_1104
	s_barrier
	s_branch .LBB0_1104
